# HGRN latent loop: batched-LDS MFMA section, no per-chunk store drain, LDS-DMA staged z/q/i rows; attention K/V staged once per workgroup through a 4-stage LDS-DMA ring
# baseline (speedup 1.0000x reference)
.LBB0_204:
	s_or_b64 exec, exec, s[4:5]
	s_waitcnt lgkmcnt(0)
	s_barrier
	ds_read_b32 v0, v173
	s_mov_b64 s[4:5], -1
	s_waitcnt lgkmcnt(0)
	v_cmp_lt_i32_e32 vcc, s68, v0
	v_readfirstlane_b32 s56, v0
	s_cbranch_vccnz .LBB0_199
	s_cmp_gt_i32 s56, 63
	s_cbranch_scc0 .LBB0_219
	s_cmpk_gt_u32 s56, 0x13f
	s_cbranch_scc0 .LBB0_216
	s_cmpk_gt_u32 s56, 0x1bf
	s_cbranch_scc0 .LBB0_262
	s_add_i32 s0, s56, 0xfffffe40
	s_lshr_b32 s2, s0, 3
	s_bfe_u32 s0, s56, 0x10002
	s_lshl_b32 s1, s2, 1
	s_or_b32 s28, s1, s0
	s_and_b32 s5, s56, 7
	s_lshl_b64 s[0:1], s[28:29], 16
	s_add_u32 s6, s59, s0
	v_mov_b32_e32 v0, v172
	v_mov_b32_e32 v2, v204
	s_addc_u32 s7, s60, s1
	s_lshl_b32 s2, s2, 8
	s_lshl_b32 s4, s5, 7
	v_ashrrev_i32_e32 v180, 4, v0
	v_and_b32_e32 v10, 15, v0
	v_lshl_add_u32 v0, v2, 5, s2
	s_lshl_b32 s2, s5, 8
	v_lshlrev_b32_e32 v6, 3, v180
	v_or_b32_e32 v164, v0, v10
	s_add_u32 s8, s3, s2
	v_ashrrev_i32_e32 v7, 31, v6
	s_addc_u32 s9, s58, 0
	v_ashrrev_i32_e32 v165, 31, v164
	v_or_b32_e32 v162, 16, v164
	v_lshlrev_b64 v[6:7], 1, v[6:7]
	v_lshlrev_b64 v[2:3], 11, v[164:165]
	v_ashrrev_i32_e32 v163, 31, v162
	v_lshl_add_u64 v[8:9], s[8:9], 0, v[6:7]
	v_lshlrev_b64 v[4:5], 11, v[162:163]
	v_lshl_add_u64 v[2:3], v[8:9], 0, v[2:3]
	global_load_dwordx4 v[62:65], v[2:3], off
	global_load_dwordx4 v[66:69], v[2:3], off offset:64
	global_load_dwordx4 v[70:73], v[2:3], off offset:128
	global_load_dwordx4 v[74:77], v[2:3], off offset:192
	v_lshl_add_u64 v[2:3], v[8:9], 0, v[4:5]
	global_load_dwordx4 v[78:81], v[2:3], off
	global_load_dwordx4 v[82:85], v[2:3], off offset:64
	global_load_dwordx4 v[86:89], v[2:3], off offset:128
	global_load_dwordx4 v[90:93], v[2:3], off offset:192
	v_lshl_add_u64 v[2:3], s[6:7], 0, v[6:7]
	v_lshlrev_b32_e32 v0, 6, v10
	v_lshl_add_u64 v[2:3], v[2:3], 0, v[0:1]
	v_add_co_u32_e32 v2, vcc, s69, v2
	v_mov_b32_e32 v34, 0
	s_nop 0
	v_addc_co_u32_e32 v3, vcc, 0, v3, vcc
	v_lshl_add_u64 v[2:3], s[6:7], 0, v[0:1]
	v_lshl_add_u64 v[168:169], v[2:3], 0, v[6:7]
	v_or_b32_e32 v2, s0, v0
	v_mov_b32_e32 v3, s1
	v_lshl_add_u64 v[2:3], v[2:3], 0, v[6:7]
	s_mov_b32 s5, 0
	v_lshl_add_u64 v[170:171], s[24:25], 0, v[2:3]
	v_mov_b32_e32 v35, v34
	v_mov_b32_e32 v36, v34
	v_mov_b32_e32 v37, v34
	v_mov_b32_e32 v46, v34
	v_mov_b32_e32 v47, v34
	v_mov_b32_e32 v48, v34
	v_mov_b32_e32 v49, v34
	v_mov_b32_e32 v50, v34
	v_mov_b32_e32 v51, v34
	v_mov_b32_e32 v52, v34
	v_mov_b32_e32 v53, v34
	v_mov_b32_e32 v54, v34
	v_mov_b32_e32 v55, v34
	v_mov_b32_e32 v56, v34
	v_mov_b32_e32 v57, v34
	v_mov_b32_e32 v58, v34
	v_mov_b32_e32 v59, v34
	v_mov_b32_e32 v60, v34
	v_mov_b32_e32 v61, v34
	v_mov_b32_e32 v94, v34
	v_mov_b32_e32 v95, v34
	v_mov_b32_e32 v96, v34
	v_mov_b32_e32 v97, v34
	v_mov_b32_e32 v42, v34
	v_mov_b32_e32 v43, v34
	v_mov_b32_e32 v44, v34
	v_mov_b32_e32 v45, v34
	v_mov_b32_e32 v38, v34
	v_mov_b32_e32 v39, v34
	v_mov_b32_e32 v40, v34
	v_mov_b32_e32 v41, v34
	v_mov_b32_e32 v30, v34
	v_mov_b32_e32 v31, v34
	v_mov_b32_e32 v32, v34
	v_mov_b32_e32 v33, v34
	v_mov_b32_e32 v26, v34
	v_mov_b32_e32 v27, v34
	v_mov_b32_e32 v28, v34
	v_mov_b32_e32 v29, v34
	v_mov_b32_e32 v22, v34
	v_mov_b32_e32 v23, v34
	v_mov_b32_e32 v24, v34
	v_mov_b32_e32 v25, v34
	v_mov_b32_e32 v18, v34
	v_mov_b32_e32 v19, v34
	v_mov_b32_e32 v20, v34
	v_mov_b32_e32 v21, v34
	v_mov_b32_e32 v14, v34
	v_mov_b32_e32 v15, v34
	v_mov_b32_e32 v16, v34
	v_mov_b32_e32 v17, v34
	v_mov_b32_e32 v10, v34
	v_mov_b32_e32 v11, v34
	v_mov_b32_e32 v12, v34
	v_mov_b32_e32 v13, v34
	v_mov_b32_e32 v6, v34
	v_mov_b32_e32 v7, v34
	v_mov_b32_e32 v8, v34
	v_mov_b32_e32 v9, v34
	v_mov_b32_e32 v2, v34
	v_mov_b32_e32 v3, v34
	v_mov_b32_e32 v4, v34
	v_mov_b32_e32 v5, v34
	v_mov_b32_e32 v166, v34
	v_mov_b32_e32 v167, v34
	v_lshrrev_b32_e32 v213, 6, v176
	v_and_b32_e32 v212, 63, v176
	v_lshlrev_b32_e32 v212, 4, v212
	v_readfirstlane_b32 s98, v213
	s_mov_b32 s101, 0
	s_mov_b32 s99, 0
	s_nop 3
	s_lshl_b32 s98, s98, 10
	s_nop 1
	v_lshl_add_u64 v[214:215], v[168:169], 0, s[98:99]
	v_lshl_add_u64 v[216:217], v[170:171], 0, s[98:99]
	s_mov_b32 m0, s98
	s_nop 0
	global_load_lds_dwordx4 v[214:215], off
	s_add_i32 m0, s98, 0x2000
	v_lshl_add_u64 v[214:215], v[214:215], 0, s[30:31]
	global_load_lds_dwordx4 v[216:217], off
	v_lshl_add_u64 v[216:217], v[216:217], 0, s[30:31]
	s_add_i32 m0, s98, 0x4000
	s_nop 0
	global_load_lds_dwordx4 v[214:215], off
	s_add_i32 m0, s98, 0x6000
	v_lshl_add_u64 v[214:215], v[214:215], 0, s[30:31]
	global_load_lds_dwordx4 v[216:217], off
	v_lshl_add_u64 v[216:217], v[216:217], 0, s[30:31]
	s_add_i32 m0, s98, 0x8000
	s_nop 0
	global_load_lds_dwordx4 v[214:215], off
	s_add_i32 m0, s98, 0xa000
	v_lshl_add_u64 v[214:215], v[214:215], 0, s[30:31]
	global_load_lds_dwordx4 v[216:217], off
	v_lshl_add_u64 v[216:217], v[216:217], 0, s[30:31]
.LBB0_209:
	s_waitcnt vmcnt(4)
	s_barrier
	s_add_i32 s99, s5, 3
	s_and_b32 s99, s99, 3
	s_lshl_b32 s99, s99, 14
	s_add_i32 s99, s99, s98
	s_mov_b32 m0, s99
	s_add_i32 s100, s5, 4
	s_cmp_lt_u32 s100, 8
	s_cselect_b32 s100, 0x2000, 0
	global_load_lds_dwordx4 v[214:215], off
	s_add_i32 m0, s99, 0x2000
	v_lshl_add_u64 v[214:215], v[214:215], 0, s[100:101]
	global_load_lds_dwordx4 v[216:217], off
	v_lshl_add_u64 v[216:217], v[216:217], 0, s[100:101]
	s_and_b32 s99, s5, 3
	s_lshl_b32 s99, s99, 14
	v_add_u32_e32 v213, s99, v212
	ds_read_b128 v[126:129], v213
	ds_read_b128 v[118:121], v213 offset:1024
	ds_read_b128 v[122:125], v213 offset:2048
	ds_read_b128 v[102:105], v213 offset:3072
	ds_read_b128 v[114:117], v213 offset:4096
	ds_read_b128 v[106:109], v213 offset:5120
	ds_read_b128 v[110:113], v213 offset:6144
	ds_read_b128 v[98:101], v213 offset:7168
	ds_read_b128 v[158:161], v213 offset:8192
	ds_read_b128 v[142:145], v213 offset:9216
	ds_read_b128 v[138:141], v213 offset:10240
	ds_read_b128 v[130:133], v213 offset:11264
	ds_read_b128 v[154:157], v213 offset:12288
	ds_read_b128 v[146:149], v213 offset:13312
	ds_read_b128 v[150:153], v213 offset:14336
	s_waitcnt lgkmcnt(14)
	v_mfma_f32_16x16x32_bf16 v[182:185], v[126:129], v[62:65], 0
	ds_read_b128 v[134:137], v213 offset:15360
	v_mfma_f32_16x16x32_bf16 v[186:189], v[126:129], v[78:81], 0
	s_waitcnt lgkmcnt(14)
	v_mfma_f32_16x16x32_bf16 v[182:185], v[118:121], v[66:69], v[182:185]
	v_mfma_f32_16x16x32_bf16 v[126:129], v[118:121], v[82:85], v[186:189]
	s_waitcnt lgkmcnt(13)
	v_mfma_f32_16x16x32_bf16 v[182:185], v[122:125], v[70:73], v[182:185]
	v_mfma_f32_16x16x32_bf16 v[118:121], v[122:125], v[86:89], v[126:129]
	s_waitcnt lgkmcnt(12)
	v_mfma_f32_16x16x32_bf16 v[182:185], v[102:105], v[74:77], v[182:185]
	v_mfma_f32_16x16x32_bf16 v[186:189], v[102:105], v[90:93], v[118:121]
	s_nop 6
	v_add_f32_e32 v0, 0xc1000000, v182
	v_min_f32_e32 v0, 0x42a00000, v0
	s_waitcnt lgkmcnt(11)
	v_mfma_f32_16x16x32_bf16 v[118:121], v[114:117], v[62:65], 0
	v_mul_f32_e32 v0, 0x3fb8aa3b, v0
	v_exp_f32_e32 v199, v0
	v_mfma_f32_16x16x32_bf16 v[122:125], v[114:117], v[78:81], 0
	v_add_f32_e32 v0, 0xc1000000, v183
	v_min_f32_e32 v0, 0x42a00000, v0
	s_waitcnt lgkmcnt(10)
	v_mfma_f32_16x16x32_bf16 v[102:105], v[106:109], v[66:69], v[118:121]
	v_mul_f32_e32 v0, 0x3fb8aa3b, v0
	v_exp_f32_e32 v201, v0
	v_mfma_f32_16x16x32_bf16 v[114:117], v[106:109], v[82:85], v[122:125]
	v_add_f32_e32 v0, 0xc1000000, v184
	v_min_f32_e32 v0, 0x42a00000, v0
	s_waitcnt lgkmcnt(9)
	v_mfma_f32_16x16x32_bf16 v[102:105], v[110:113], v[70:73], v[102:105]
	v_mul_f32_e32 v0, 0x3fb8aa3b, v0
	v_exp_f32_e32 v203, v0
	v_mfma_f32_16x16x32_bf16 v[106:109], v[110:113], v[86:89], v[114:117]
	v_add_f32_e32 v0, 0xc1000000, v185
	v_min_f32_e32 v0, 0x42a00000, v0
	s_waitcnt lgkmcnt(8)
	v_mfma_f32_16x16x32_bf16 v[190:193], v[98:101], v[74:77], v[102:105]
	v_mul_f32_e32 v0, 0x3fb8aa3b, v0
	v_exp_f32_e32 v207, v0
	v_mfma_f32_16x16x32_bf16 v[194:197], v[98:101], v[90:93], v[106:109]
	v_add_f32_e32 v0, 0xc1000000, v186
	v_min_f32_e32 v0, 0x42a00000, v0
	v_mul_f32_e32 v0, 0x3fb8aa3b, v0
	v_exp_f32_e32 v198, v0
	v_add_f32_e32 v0, 0xc1000000, v187
	v_min_f32_e32 v0, 0x42a00000, v0
	v_mul_f32_e32 v0, 0x3fb8aa3b, v0
	v_exp_f32_e32 v200, v0
	v_add_f32_e32 v0, 0xc1000000, v188
	v_min_f32_e32 v0, 0x42a00000, v0
	v_mul_f32_e32 v0, 0x3fb8aa3b, v0
	v_exp_f32_e32 v202, v0
	v_add_f32_e32 v0, 0xc1000000, v189
	v_min_f32_e32 v0, 0x42a00000, v0
	v_mul_f32_e32 v0, 0x3fb8aa3b, v0
	v_exp_f32_e32 v206, v0
	v_add_f32_e32 v0, 0xc1000000, v190
	v_min_f32_e32 v0, 0x42a00000, v0
	v_mul_f32_e32 v0, 0x3fb8aa3b, v0
	v_exp_f32_e32 v209, v0
	v_add_f32_e32 v0, 0xc1000000, v191
	v_min_f32_e32 v0, 0x42a00000, v0
	v_mul_f32_e32 v0, 0x3fb8aa3b, v0
	v_exp_f32_e32 v191, v0
	v_add_f32_e32 v0, 0xc1000000, v192
	v_min_f32_e32 v0, 0x42a00000, v0
	v_mul_f32_e32 v0, 0x3fb8aa3b, v0
	v_exp_f32_e32 v211, v0
	v_add_f32_e32 v0, 0xc1000000, v193
	v_min_f32_e32 v0, 0x42a00000, v0
	v_mul_f32_e32 v0, 0x3fb8aa3b, v0
	v_exp_f32_e32 v193, v0
	v_add_f32_e32 v0, 0xc1000000, v194
	v_min_f32_e32 v0, 0x42a00000, v0
	v_mul_f32_e32 v0, 0x3fb8aa3b, v0
	v_exp_f32_e32 v208, v0
	v_add_f32_e32 v0, 0xc1000000, v195
	v_min_f32_e32 v0, 0x42a00000, v0
	v_mul_f32_e32 v0, 0x3fb8aa3b, v0
	v_exp_f32_e32 v190, v0
	v_add_f32_e32 v0, 0xc1000000, v196
	v_min_f32_e32 v0, 0x42a00000, v0
	v_mul_f32_e32 v0, 0x3fb8aa3b, v0
	v_exp_f32_e32 v210, v0
	v_add_f32_e32 v0, 0xc1000000, v197
	v_pk_add_f32 v[166:167], v[166:167], v[198:199]
	v_min_f32_e32 v0, 0x42a00000, v0
	v_pk_add_f32 v[166:167], v[200:201], v[166:167]
	v_mul_f32_e32 v0, 0x3fb8aa3b, v0
	v_pk_add_f32 v[166:167], v[202:203], v[166:167]
	v_exp_f32_e32 v192, v0
	v_pk_add_f32 v[166:167], v[206:207], v[166:167]
	v_cvt_pk_bf16_f32 v182, v199, v201
	v_cvt_pk_bf16_f32 v183, v203, v207
	v_cvt_pk_bf16_f32 v184, v209, v191
	v_cvt_pk_bf16_f32 v185, v211, v193
	v_cvt_pk_bf16_f32 v186, v198, v200
	s_nop 0
	v_pk_add_f32 v[166:167], v[166:167], v[208:209]
	s_waitcnt lgkmcnt(7)
	v_mfma_f32_16x16x32_bf16 v[94:97], v[158:161], v[182:185], v[94:97]
	v_add_f32_e64 v166, v190, v166
	v_add_f32_e64 v167, v191, v167
	v_cvt_pk_bf16_f32 v187, v202, v206
	v_cvt_pk_bf16_f32 v188, v208, v190
	v_cvt_pk_bf16_f32 v189, v210, v192
	s_waitcnt lgkmcnt(6)
	v_mfma_f32_16x16x32_bf16 v[58:61], v[142:145], v[182:185], v[58:61]
	v_add_f32_e64 v166, v210, v166
	v_add_f32_e64 v167, v211, v167
	v_mfma_f32_16x16x32_bf16 v[30:33], v[158:161], v[186:189], v[30:33]
	v_add_f32_e64 v166, v192, v166
	v_add_f32_e64 v167, v193, v167
	v_mfma_f32_16x16x32_bf16 v[26:29], v[142:145], v[186:189], v[26:29]
	s_waitcnt lgkmcnt(5)
	v_mfma_f32_16x16x32_bf16 v[54:57], v[138:141], v[182:185], v[54:57]
	v_mfma_f32_16x16x32_bf16 v[22:25], v[138:141], v[186:189], v[22:25]
	s_waitcnt lgkmcnt(4)
	v_mfma_f32_16x16x32_bf16 v[50:53], v[130:133], v[182:185], v[50:53]
	v_mfma_f32_16x16x32_bf16 v[18:21], v[130:133], v[186:189], v[18:21]
	s_waitcnt lgkmcnt(3)
	v_mfma_f32_16x16x32_bf16 v[46:49], v[154:157], v[182:185], v[46:49]
	v_mfma_f32_16x16x32_bf16 v[14:17], v[154:157], v[186:189], v[14:17]
	s_waitcnt lgkmcnt(2)
	v_mfma_f32_16x16x32_bf16 v[34:37], v[146:149], v[182:185], v[34:37]
	v_mfma_f32_16x16x32_bf16 v[10:13], v[146:149], v[186:189], v[10:13]
	s_waitcnt lgkmcnt(1)
	v_mfma_f32_16x16x32_bf16 v[42:45], v[150:153], v[182:185], v[42:45]
	v_mfma_f32_16x16x32_bf16 v[6:9], v[150:153], v[186:189], v[6:9]
	s_waitcnt lgkmcnt(0)
	v_mfma_f32_16x16x32_bf16 v[38:41], v[134:137], v[182:185], v[38:41]
	v_mfma_f32_16x16x32_bf16 v[2:5], v[134:137], v[186:189], v[2:5]
	s_add_i32 s5, s5, 1
	s_cmp_lt_u32 s5, 8
	s_cbranch_scc1 .LBB0_209
	s_waitcnt vmcnt(0)
	v_and_b32_e32 v62, 64, v175
	v_xor_b32_e32 v0, 16, v175
	v_add_u32_e32 v62, 64, v62
	v_cmp_lt_i32_e32 vcc, v0, v62
	v_xor_b32_e32 v64, 32, v175
	s_lshl_b32 s0, s4, 1
	v_cndmask_b32_e32 v0, v175, v0, vcc
	v_lshlrev_b32_e32 v0, 2, v0
	ds_bpermute_b32 v63, v0, v167
	v_cmp_lt_i32_e32 vcc, v64, v62
	s_add_u32 s0, s61, s0
	s_addc_u32 s1, s62, 0
	v_cndmask_b32_e32 v62, v175, v64, vcc
	v_lshlrev_b32_e32 v68, 2, v62
	s_waitcnt lgkmcnt(0)
	v_add_f32_e32 v62, v167, v63
	ds_bpermute_b32 v63, v68, v62
	ds_bpermute_b32 v0, v0, v166
	s_mov_b64 s[50:51], -1
	s_waitcnt lgkmcnt(1)
	v_add_f32_e32 v64, v62, v63
	v_div_scale_f32 v65, s[4:5], v64, v64, 1.0
	v_rcp_f32_e32 v66, v65
	v_lshlrev_b32_e32 v62, 2, v180
	v_ashrrev_i32_e32 v63, 31, v62
	v_lshl_add_u64 v[62:63], v[62:63], 1, s[0:1]
	v_fma_f32 v67, -v65, v66, 1.0
	v_fmac_f32_e32 v66, v67, v66
	v_div_scale_f32 v67, vcc, 1.0, v64, 1.0
	v_mul_f32_e32 v69, v67, v66
	v_fma_f32 v70, -v65, v69, v67
	v_fmac_f32_e32 v69, v70, v66
	v_fma_f32 v65, -v65, v69, v67
	v_div_fmas_f32 v65, v65, v66, v69
	v_div_fixup_f32 v69, v65, v64, 1.0
	v_lshlrev_b64 v[64:65], 12, v[164:165]
	v_mul_f32_e32 v66, v94, v69
	v_mul_f32_e32 v67, v95, v69
	v_lshl_add_u64 v[64:65], v[62:63], 0, v[64:65]
	v_cvt_pk_bf16_f32 v66, v66, v67
	v_mul_f32_e32 v67, v96, v69
	v_mul_f32_e32 v58, v58, v69
	v_mul_f32_e32 v59, v59, v69
	v_mul_f32_e32 v70, v97, v69
	v_cvt_pk_bf16_f32 v67, v67, v70
	global_store_dwordx2 v[64:65], v[66:67], off
	v_cvt_pk_bf16_f32 v58, v58, v59
	v_mul_f32_e32 v59, v60, v69
	v_mul_f32_e32 v54, v54, v69
	v_mul_f32_e32 v55, v55, v69
	v_mul_f32_e32 v60, v61, v69
	v_cvt_pk_bf16_f32 v59, v59, v60
	global_store_dwordx2 v[64:65], v[58:59], off offset:32
	v_cvt_pk_bf16_f32 v54, v54, v55
	v_mul_f32_e32 v55, v56, v69
	v_mul_f32_e32 v50, v50, v69
	v_mul_f32_e32 v51, v51, v69
	v_mul_f32_e32 v56, v57, v69
	v_cvt_pk_bf16_f32 v55, v55, v56
	global_store_dwordx2 v[64:65], v[54:55], off offset:64
	v_cvt_pk_bf16_f32 v50, v50, v51
	v_mul_f32_e32 v51, v52, v69
	v_mul_f32_e32 v46, v46, v69
	v_mul_f32_e32 v47, v47, v69
	v_mul_f32_e32 v52, v53, v69
	v_cvt_pk_bf16_f32 v51, v51, v52
	global_store_dwordx2 v[64:65], v[50:51], off offset:96
	v_cvt_pk_bf16_f32 v46, v46, v47
	v_mul_f32_e32 v47, v48, v69
	v_mul_f32_e32 v34, v34, v69
	v_mul_f32_e32 v35, v35, v69
	v_mul_f32_e32 v48, v49, v69
	v_cvt_pk_bf16_f32 v47, v47, v48
	global_store_dwordx2 v[64:65], v[46:47], off offset:128
	v_cvt_pk_bf16_f32 v34, v34, v35
	v_mul_f32_e32 v35, v36, v69
	v_mul_f32_e32 v36, v37, v69
	v_cvt_pk_bf16_f32 v35, v35, v36
	global_store_dwordx2 v[64:65], v[34:35], off offset:160
	v_mul_f32_e32 v34, v42, v69
	v_mul_f32_e32 v35, v43, v69
	v_cvt_pk_bf16_f32 v34, v34, v35
	v_mul_f32_e32 v35, v44, v69
	v_mul_f32_e32 v36, v45, v69
	v_cvt_pk_bf16_f32 v35, v35, v36
	s_waitcnt lgkmcnt(0)
	v_add_f32_e32 v0, v166, v0
	global_store_dwordx2 v[64:65], v[34:35], off offset:192
	ds_bpermute_b32 v35, v68, v0
	v_mul_f32_e32 v34, v38, v69
	v_mul_f32_e32 v36, v39, v69
	v_cvt_pk_bf16_f32 v34, v34, v36
	v_mul_f32_e32 v36, v40, v69
	s_waitcnt lgkmcnt(0)
	v_add_f32_e32 v0, v0, v35
	v_div_scale_f32 v37, s[0:1], v0, v0, 1.0
	v_rcp_f32_e32 v38, v37
	v_mul_f32_e32 v35, v41, v69
	v_cvt_pk_bf16_f32 v35, v36, v35
	global_store_dwordx2 v[64:65], v[34:35], off offset:224
	v_fma_f32 v34, -v37, v38, 1.0
	v_fmac_f32_e32 v38, v34, v38
	v_div_scale_f32 v34, vcc, 1.0, v0, 1.0
	v_mul_f32_e32 v35, v34, v38
	v_fma_f32 v36, -v37, v35, v34
	v_fmac_f32_e32 v35, v36, v38
	v_fma_f32 v34, -v37, v35, v34
	v_div_fmas_f32 v34, v34, v38, v35
	v_div_fixup_f32 v0, v34, v0, 1.0
	v_lshlrev_b64 v[34:35], 12, v[162:163]
	v_mul_f32_e32 v30, v30, v0
	v_mul_f32_e32 v31, v31, v0
	v_lshl_add_u64 v[78:79], v[62:63], 0, v[34:35]
	v_cvt_pk_bf16_f32 v30, v30, v31
	v_mul_f32_e32 v31, v32, v0
	v_mul_f32_e32 v26, v26, v0
	v_mul_f32_e32 v27, v27, v0
	v_mul_f32_e32 v32, v33, v0
	v_cvt_pk_bf16_f32 v31, v31, v32
	global_store_dwordx2 v[78:79], v[30:31], off
	v_cvt_pk_bf16_f32 v26, v26, v27
	v_mul_f32_e32 v27, v28, v0
	v_mul_f32_e32 v22, v22, v0
	v_mul_f32_e32 v23, v23, v0
	v_mul_f32_e32 v28, v29, v0
	v_cvt_pk_bf16_f32 v27, v27, v28
	global_store_dwordx2 v[78:79], v[26:27], off offset:32
	v_cvt_pk_bf16_f32 v22, v22, v23
	v_mul_f32_e32 v23, v24, v0
	v_mul_f32_e32 v18, v18, v0
	v_mul_f32_e32 v19, v19, v0
	v_mul_f32_e32 v24, v25, v0
	v_cvt_pk_bf16_f32 v23, v23, v24
	global_store_dwordx2 v[78:79], v[22:23], off offset:64
	v_cvt_pk_bf16_f32 v18, v18, v19
	v_mul_f32_e32 v19, v20, v0
	v_mul_f32_e32 v14, v14, v0
	v_mul_f32_e32 v15, v15, v0
	v_mul_f32_e32 v20, v21, v0
	v_cvt_pk_bf16_f32 v19, v19, v20
	global_store_dwordx2 v[78:79], v[18:19], off offset:96
	v_cvt_pk_bf16_f32 v14, v14, v15
	v_mul_f32_e32 v15, v16, v0
	v_mul_f32_e32 v10, v10, v0
	v_mul_f32_e32 v11, v11, v0
	v_mul_f32_e32 v16, v17, v0
	v_cvt_pk_bf16_f32 v15, v15, v16
	global_store_dwordx2 v[78:79], v[14:15], off offset:128
	v_cvt_pk_bf16_f32 v10, v10, v11
	v_mul_f32_e32 v11, v12, v0
	v_mul_f32_e32 v6, v6, v0
	v_mul_f32_e32 v7, v7, v0
	v_mul_f32_e32 v12, v13, v0
	v_cvt_pk_bf16_f32 v11, v11, v12
	global_store_dwordx2 v[78:79], v[10:11], off offset:160
	v_cvt_pk_bf16_f32 v6, v6, v7
	v_mul_f32_e32 v7, v8, v0
	v_mul_f32_e32 v2, v2, v0
	v_mul_f32_e32 v8, v9, v0
	v_cvt_pk_bf16_f32 v7, v7, v8
	global_store_dwordx2 v[78:79], v[6:7], off offset:192
	v_mul_f32_e32 v3, v3, v0
	v_cvt_pk_bf16_f32 v80, v2, v3
	v_mul_f32_e32 v2, v4, v0
	v_mul_f32_e32 v0, v5, v0
	v_cvt_pk_bf16_f32 v81, v2, v0

.LBB0_212:
	s_sub_i32 s0, s56, 64
	s_lshr_b32 s2, s0, 5
	s_lshr_b32 s0, s56, 2
	s_bfe_u32 s0, s0, 0x10002
	s_lshl_b32 s1, s2, 1
	s_or_b32 s0, s1, s0
	s_bfe_u32 s5, s56, 0x30002
	s_mul_i32 s9, s0, 0x50000
	s_mul_hi_u32 s8, s0, 0x50000
	s_add_u32 s0, s63, s9
	s_addc_u32 s1, s64, s8
	s_lshl_b32 s4, s56, 8
	s_lshl_b32 s2, s2, 10
	s_and_b32 s4, s4, 0x300
	v_mov_b32_e32 v0, v172
	v_mov_b32_e32 v2, v204
	s_or_b32 s2, s2, s4
	s_addk_i32 s2, 0x1000
	v_ashrrev_i32_e32 v180, 4, v0
	v_and_b32_e32 v10, 15, v0
	v_lshl_add_u32 v0, v2, 5, s2
	s_lshl_b32 s4, s5, 7
	s_lshl_b32 s2, s5, 8
	v_lshlrev_b32_e32 v6, 3, v180
	v_or_b32_e32 v164, v0, v10
	s_add_u32 s6, s3, s2
	v_ashrrev_i32_e32 v7, 31, v6
	s_addc_u32 s7, s58, 0
	v_ashrrev_i32_e32 v165, 31, v164
	v_or_b32_e32 v162, 16, v164
	v_lshlrev_b64 v[6:7], 1, v[6:7]
	v_lshlrev_b64 v[2:3], 11, v[164:165]
	v_ashrrev_i32_e32 v163, 31, v162
	v_lshl_add_u64 v[8:9], s[6:7], 0, v[6:7]
	v_lshlrev_b64 v[4:5], 11, v[162:163]
	v_lshl_add_u64 v[2:3], v[8:9], 0, v[2:3]
	global_load_dwordx4 v[62:65], v[2:3], off
	global_load_dwordx4 v[66:69], v[2:3], off offset:64
	global_load_dwordx4 v[70:73], v[2:3], off offset:128
	global_load_dwordx4 v[74:77], v[2:3], off offset:192
	v_lshl_add_u64 v[2:3], v[8:9], 0, v[4:5]
	global_load_dwordx4 v[78:81], v[2:3], off
	global_load_dwordx4 v[82:85], v[2:3], off offset:64
	global_load_dwordx4 v[86:89], v[2:3], off offset:128
	global_load_dwordx4 v[90:93], v[2:3], off offset:192
	v_lshl_add_u64 v[2:3], s[0:1], 0, v[6:7]
	v_lshlrev_b32_e32 v0, 6, v10
	v_lshl_add_u64 v[2:3], v[2:3], 0, v[0:1]
	v_add_co_u32_e32 v2, vcc, s69, v2
	v_mov_b32_e32 v34, 0
	s_nop 0
	v_addc_co_u32_e32 v3, vcc, 0, v3, vcc
	v_lshl_add_u64 v[2:3], s[0:1], 0, v[0:1]
	v_lshl_add_u64 v[168:169], v[2:3], 0, v[6:7]
	v_or_b32_e32 v2, s9, v0
	v_mov_b32_e32 v3, s8
	v_lshl_add_u64 v[2:3], v[2:3], 0, v[6:7]
	s_mov_b32 s5, 0
	v_lshl_add_u64 v[170:171], s[26:27], 0, v[2:3]
	v_mov_b32_e32 v35, v34
	v_mov_b32_e32 v36, v34
	v_mov_b32_e32 v37, v34
	v_mov_b32_e32 v46, v34
	v_mov_b32_e32 v47, v34
	v_mov_b32_e32 v48, v34
	v_mov_b32_e32 v49, v34
	v_mov_b32_e32 v50, v34
	v_mov_b32_e32 v51, v34
	v_mov_b32_e32 v52, v34
	v_mov_b32_e32 v53, v34
	v_mov_b32_e32 v54, v34
	v_mov_b32_e32 v55, v34
	v_mov_b32_e32 v56, v34
	v_mov_b32_e32 v57, v34
	v_mov_b32_e32 v58, v34
	v_mov_b32_e32 v59, v34
	v_mov_b32_e32 v60, v34
	v_mov_b32_e32 v61, v34
	v_mov_b32_e32 v94, v34
	v_mov_b32_e32 v95, v34
	v_mov_b32_e32 v96, v34
	v_mov_b32_e32 v97, v34
	v_mov_b32_e32 v42, v34
	v_mov_b32_e32 v43, v34
	v_mov_b32_e32 v44, v34
	v_mov_b32_e32 v45, v34
	v_mov_b32_e32 v38, v34
	v_mov_b32_e32 v39, v34
	v_mov_b32_e32 v40, v34
	v_mov_b32_e32 v41, v34
	v_mov_b32_e32 v30, v34
	v_mov_b32_e32 v31, v34
	v_mov_b32_e32 v32, v34
	v_mov_b32_e32 v33, v34
	v_mov_b32_e32 v26, v34
	v_mov_b32_e32 v27, v34
	v_mov_b32_e32 v28, v34
	v_mov_b32_e32 v29, v34
	v_mov_b32_e32 v22, v34
	v_mov_b32_e32 v23, v34
	v_mov_b32_e32 v24, v34
	v_mov_b32_e32 v25, v34
	v_mov_b32_e32 v18, v34
	v_mov_b32_e32 v19, v34
	v_mov_b32_e32 v20, v34
	v_mov_b32_e32 v21, v34
	v_mov_b32_e32 v14, v34
	v_mov_b32_e32 v15, v34
	v_mov_b32_e32 v16, v34
	v_mov_b32_e32 v17, v34
	v_mov_b32_e32 v10, v34
	v_mov_b32_e32 v11, v34
	v_mov_b32_e32 v12, v34
	v_mov_b32_e32 v13, v34
	v_mov_b32_e32 v6, v34
	v_mov_b32_e32 v7, v34
	v_mov_b32_e32 v8, v34
	v_mov_b32_e32 v9, v34
	v_mov_b32_e32 v2, v34
	v_mov_b32_e32 v3, v34
	v_mov_b32_e32 v4, v34
	v_mov_b32_e32 v5, v34
	v_mov_b32_e32 v166, v34
	v_mov_b32_e32 v167, v34
	v_lshrrev_b32_e32 v213, 6, v176
	v_and_b32_e32 v212, 63, v176
	v_lshlrev_b32_e32 v212, 4, v212
	v_readfirstlane_b32 s98, v213
	s_mov_b32 s101, 0
	s_mov_b32 s99, 0
	s_nop 3
	s_lshl_b32 s98, s98, 10
	s_nop 1
	v_lshl_add_u64 v[214:215], v[168:169], 0, s[98:99]
	v_lshl_add_u64 v[216:217], v[170:171], 0, s[98:99]
	s_mov_b32 m0, s98
	s_nop 0
	global_load_lds_dwordx4 v[214:215], off
	s_add_i32 m0, s98, 0x2000
	v_lshl_add_u64 v[214:215], v[214:215], 0, s[30:31]
	global_load_lds_dwordx4 v[216:217], off
	v_lshl_add_u64 v[216:217], v[216:217], 0, s[30:31]
	s_add_i32 m0, s98, 0x4000
	s_nop 0
	global_load_lds_dwordx4 v[214:215], off
	s_add_i32 m0, s98, 0x6000
	v_lshl_add_u64 v[214:215], v[214:215], 0, s[30:31]
	global_load_lds_dwordx4 v[216:217], off
	v_lshl_add_u64 v[216:217], v[216:217], 0, s[30:31]
	s_add_i32 m0, s98, 0x8000
	s_nop 0
	global_load_lds_dwordx4 v[214:215], off
	s_add_i32 m0, s98, 0xa000
	v_lshl_add_u64 v[214:215], v[214:215], 0, s[30:31]
	global_load_lds_dwordx4 v[216:217], off
	v_lshl_add_u64 v[216:217], v[216:217], 0, s[30:31]
.LBB0_213:
	s_waitcnt vmcnt(4)
	s_barrier
	s_add_i32 s99, s5, 3
	s_and_b32 s99, s99, 3
	s_lshl_b32 s99, s99, 14
	s_add_i32 s99, s99, s98
	s_mov_b32 m0, s99
	s_add_i32 s100, s5, 4
	s_cmp_lt_u32 s100, 40
	s_cselect_b32 s100, 0x2000, 0
	global_load_lds_dwordx4 v[214:215], off
	s_add_i32 m0, s99, 0x2000
	v_lshl_add_u64 v[214:215], v[214:215], 0, s[100:101]
	global_load_lds_dwordx4 v[216:217], off
	v_lshl_add_u64 v[216:217], v[216:217], 0, s[100:101]
	s_and_b32 s99, s5, 3
	s_lshl_b32 s99, s99, 14
	v_add_u32_e32 v213, s99, v212
	ds_read_b128 v[126:129], v213
	ds_read_b128 v[118:121], v213 offset:1024
	ds_read_b128 v[122:125], v213 offset:2048
	ds_read_b128 v[102:105], v213 offset:3072
	ds_read_b128 v[114:117], v213 offset:4096
	ds_read_b128 v[106:109], v213 offset:5120
	ds_read_b128 v[110:113], v213 offset:6144
	ds_read_b128 v[98:101], v213 offset:7168
	ds_read_b128 v[158:161], v213 offset:8192
	ds_read_b128 v[142:145], v213 offset:9216
	ds_read_b128 v[138:141], v213 offset:10240
	ds_read_b128 v[130:133], v213 offset:11264
	ds_read_b128 v[154:157], v213 offset:12288
	ds_read_b128 v[146:149], v213 offset:13312
	ds_read_b128 v[150:153], v213 offset:14336
	s_waitcnt lgkmcnt(14)
	v_mfma_f32_16x16x32_bf16 v[182:185], v[126:129], v[62:65], 0
	ds_read_b128 v[134:137], v213 offset:15360
	v_mfma_f32_16x16x32_bf16 v[186:189], v[126:129], v[78:81], 0
	s_waitcnt lgkmcnt(14)
	v_mfma_f32_16x16x32_bf16 v[182:185], v[118:121], v[66:69], v[182:185]
	v_mfma_f32_16x16x32_bf16 v[126:129], v[118:121], v[82:85], v[186:189]
	s_waitcnt lgkmcnt(13)
	v_mfma_f32_16x16x32_bf16 v[182:185], v[122:125], v[70:73], v[182:185]
	v_mfma_f32_16x16x32_bf16 v[118:121], v[122:125], v[86:89], v[126:129]
	s_waitcnt lgkmcnt(12)
	v_mfma_f32_16x16x32_bf16 v[182:185], v[102:105], v[74:77], v[182:185]
	v_mfma_f32_16x16x32_bf16 v[186:189], v[102:105], v[90:93], v[118:121]
	s_nop 6
	v_add_f32_e32 v0, 0xc1000000, v182
	v_min_f32_e32 v0, 0x42a00000, v0
	s_waitcnt lgkmcnt(11)
	v_mfma_f32_16x16x32_bf16 v[118:121], v[114:117], v[62:65], 0
	v_mul_f32_e32 v0, 0x3fb8aa3b, v0
	v_exp_f32_e32 v199, v0
	v_mfma_f32_16x16x32_bf16 v[122:125], v[114:117], v[78:81], 0
	v_add_f32_e32 v0, 0xc1000000, v183
	v_min_f32_e32 v0, 0x42a00000, v0
	s_waitcnt lgkmcnt(10)
	v_mfma_f32_16x16x32_bf16 v[102:105], v[106:109], v[66:69], v[118:121]
	v_mul_f32_e32 v0, 0x3fb8aa3b, v0
	v_exp_f32_e32 v201, v0
	v_mfma_f32_16x16x32_bf16 v[114:117], v[106:109], v[82:85], v[122:125]
	v_add_f32_e32 v0, 0xc1000000, v184
	v_min_f32_e32 v0, 0x42a00000, v0
	s_waitcnt lgkmcnt(9)
	v_mfma_f32_16x16x32_bf16 v[102:105], v[110:113], v[70:73], v[102:105]
	v_mul_f32_e32 v0, 0x3fb8aa3b, v0
	v_exp_f32_e32 v203, v0
	v_mfma_f32_16x16x32_bf16 v[106:109], v[110:113], v[86:89], v[114:117]
	v_add_f32_e32 v0, 0xc1000000, v185
	v_min_f32_e32 v0, 0x42a00000, v0
	s_waitcnt lgkmcnt(8)
	v_mfma_f32_16x16x32_bf16 v[190:193], v[98:101], v[74:77], v[102:105]
	v_mul_f32_e32 v0, 0x3fb8aa3b, v0
	v_exp_f32_e32 v207, v0
	v_mfma_f32_16x16x32_bf16 v[194:197], v[98:101], v[90:93], v[106:109]
	v_add_f32_e32 v0, 0xc1000000, v186
	v_min_f32_e32 v0, 0x42a00000, v0
	v_mul_f32_e32 v0, 0x3fb8aa3b, v0
	v_exp_f32_e32 v198, v0
	v_add_f32_e32 v0, 0xc1000000, v187
	v_min_f32_e32 v0, 0x42a00000, v0
	v_mul_f32_e32 v0, 0x3fb8aa3b, v0
	v_exp_f32_e32 v200, v0
	v_add_f32_e32 v0, 0xc1000000, v188
	v_min_f32_e32 v0, 0x42a00000, v0
	v_mul_f32_e32 v0, 0x3fb8aa3b, v0
	v_exp_f32_e32 v202, v0
	v_add_f32_e32 v0, 0xc1000000, v189
	v_min_f32_e32 v0, 0x42a00000, v0
	v_mul_f32_e32 v0, 0x3fb8aa3b, v0
	v_exp_f32_e32 v206, v0
	v_add_f32_e32 v0, 0xc1000000, v190
	v_min_f32_e32 v0, 0x42a00000, v0
	v_mul_f32_e32 v0, 0x3fb8aa3b, v0
	v_exp_f32_e32 v209, v0
	v_add_f32_e32 v0, 0xc1000000, v191
	v_min_f32_e32 v0, 0x42a00000, v0
	v_mul_f32_e32 v0, 0x3fb8aa3b, v0
	v_exp_f32_e32 v191, v0
	v_add_f32_e32 v0, 0xc1000000, v192
	v_min_f32_e32 v0, 0x42a00000, v0
	v_mul_f32_e32 v0, 0x3fb8aa3b, v0
	v_exp_f32_e32 v211, v0
	v_add_f32_e32 v0, 0xc1000000, v193
	v_min_f32_e32 v0, 0x42a00000, v0
	v_mul_f32_e32 v0, 0x3fb8aa3b, v0
	v_exp_f32_e32 v193, v0
	v_add_f32_e32 v0, 0xc1000000, v194
	v_min_f32_e32 v0, 0x42a00000, v0
	v_mul_f32_e32 v0, 0x3fb8aa3b, v0
	v_exp_f32_e32 v208, v0
	v_add_f32_e32 v0, 0xc1000000, v195
	v_min_f32_e32 v0, 0x42a00000, v0
	v_mul_f32_e32 v0, 0x3fb8aa3b, v0
	v_exp_f32_e32 v190, v0
	v_add_f32_e32 v0, 0xc1000000, v196
	v_min_f32_e32 v0, 0x42a00000, v0
	v_mul_f32_e32 v0, 0x3fb8aa3b, v0
	v_exp_f32_e32 v210, v0
	v_add_f32_e32 v0, 0xc1000000, v197
	v_pk_add_f32 v[166:167], v[166:167], v[198:199]
	v_min_f32_e32 v0, 0x42a00000, v0
	v_pk_add_f32 v[166:167], v[200:201], v[166:167]
	v_mul_f32_e32 v0, 0x3fb8aa3b, v0
	v_pk_add_f32 v[166:167], v[202:203], v[166:167]
	v_exp_f32_e32 v192, v0
	v_pk_add_f32 v[166:167], v[206:207], v[166:167]
	v_cvt_pk_bf16_f32 v182, v199, v201
	v_cvt_pk_bf16_f32 v183, v203, v207
	v_cvt_pk_bf16_f32 v184, v209, v191
	v_cvt_pk_bf16_f32 v185, v211, v193
	v_cvt_pk_bf16_f32 v186, v198, v200
	s_nop 0
	v_pk_add_f32 v[166:167], v[166:167], v[208:209]
	s_waitcnt lgkmcnt(7)
	v_mfma_f32_16x16x32_bf16 v[94:97], v[158:161], v[182:185], v[94:97]
	v_add_f32_e64 v166, v190, v166
	v_add_f32_e64 v167, v191, v167
	v_cvt_pk_bf16_f32 v187, v202, v206
	v_cvt_pk_bf16_f32 v188, v208, v190
	v_cvt_pk_bf16_f32 v189, v210, v192
	s_waitcnt lgkmcnt(6)
	v_mfma_f32_16x16x32_bf16 v[58:61], v[142:145], v[182:185], v[58:61]
	v_add_f32_e64 v166, v210, v166
	v_add_f32_e64 v167, v211, v167
	v_mfma_f32_16x16x32_bf16 v[30:33], v[158:161], v[186:189], v[30:33]
	v_add_f32_e64 v166, v192, v166
	v_add_f32_e64 v167, v193, v167
	v_mfma_f32_16x16x32_bf16 v[26:29], v[142:145], v[186:189], v[26:29]
	s_waitcnt lgkmcnt(5)
	v_mfma_f32_16x16x32_bf16 v[54:57], v[138:141], v[182:185], v[54:57]
	v_mfma_f32_16x16x32_bf16 v[22:25], v[138:141], v[186:189], v[22:25]
	s_waitcnt lgkmcnt(4)
	v_mfma_f32_16x16x32_bf16 v[50:53], v[130:133], v[182:185], v[50:53]
	v_mfma_f32_16x16x32_bf16 v[18:21], v[130:133], v[186:189], v[18:21]
	s_waitcnt lgkmcnt(3)
	v_mfma_f32_16x16x32_bf16 v[46:49], v[154:157], v[182:185], v[46:49]
	v_mfma_f32_16x16x32_bf16 v[14:17], v[154:157], v[186:189], v[14:17]
	s_waitcnt lgkmcnt(2)
	v_mfma_f32_16x16x32_bf16 v[34:37], v[146:149], v[182:185], v[34:37]
	v_mfma_f32_16x16x32_bf16 v[10:13], v[146:149], v[186:189], v[10:13]
	s_waitcnt lgkmcnt(1)
	v_mfma_f32_16x16x32_bf16 v[42:45], v[150:153], v[182:185], v[42:45]
	v_mfma_f32_16x16x32_bf16 v[6:9], v[150:153], v[186:189], v[6:9]
	s_waitcnt lgkmcnt(0)
	v_mfma_f32_16x16x32_bf16 v[38:41], v[134:137], v[182:185], v[38:41]
	v_mfma_f32_16x16x32_bf16 v[2:5], v[134:137], v[186:189], v[2:5]
	s_add_i32 s5, s5, 1
	s_cmp_lt_u32 s5, 40
	s_cbranch_scc1 .LBB0_213
	s_waitcnt vmcnt(0)
	v_and_b32_e32 v62, 64, v175
	v_xor_b32_e32 v0, 16, v175
	v_add_u32_e32 v62, 64, v62
	v_cmp_lt_i32_e32 vcc, v0, v62
	v_xor_b32_e32 v64, 32, v175
	s_lshl_b32 s0, s4, 1
	v_cndmask_b32_e32 v0, v175, v0, vcc
	v_lshlrev_b32_e32 v0, 2, v0
	ds_bpermute_b32 v63, v0, v167
	v_cmp_lt_i32_e32 vcc, v64, v62
	s_add_u32 s0, s61, s0
	s_addc_u32 s1, s62, 0
	v_cndmask_b32_e32 v62, v175, v64, vcc
	v_lshlrev_b32_e32 v68, 2, v62
	s_waitcnt lgkmcnt(0)
	v_add_f32_e32 v62, v167, v63
	ds_bpermute_b32 v63, v68, v62
	ds_bpermute_b32 v0, v0, v166
	s_waitcnt lgkmcnt(1)
	v_add_f32_e32 v64, v62, v63
	v_div_scale_f32 v65, s[4:5], v64, v64, 1.0
	v_rcp_f32_e32 v66, v65
	v_lshlrev_b32_e32 v62, 2, v180
	v_ashrrev_i32_e32 v63, 31, v62
	v_lshl_add_u64 v[62:63], v[62:63], 1, s[0:1]
	v_fma_f32 v67, -v65, v66, 1.0
	v_fmac_f32_e32 v66, v67, v66
	v_div_scale_f32 v67, vcc, 1.0, v64, 1.0
	v_mul_f32_e32 v69, v67, v66
	v_fma_f32 v70, -v65, v69, v67
	v_fmac_f32_e32 v69, v70, v66
	v_fma_f32 v65, -v65, v69, v67
	v_div_fmas_f32 v65, v65, v66, v69
	v_div_fixup_f32 v69, v65, v64, 1.0
	v_lshlrev_b64 v[64:65], 12, v[164:165]
	v_mul_f32_e32 v66, v94, v69
	v_mul_f32_e32 v67, v95, v69
	v_lshl_add_u64 v[64:65], v[62:63], 0, v[64:65]
	v_cvt_pk_bf16_f32 v66, v66, v67
	v_mul_f32_e32 v67, v96, v69
	v_mul_f32_e32 v58, v58, v69
	v_mul_f32_e32 v59, v59, v69
	v_mul_f32_e32 v70, v97, v69
	v_cvt_pk_bf16_f32 v67, v67, v70
	global_store_dwordx2 v[64:65], v[66:67], off
	v_cvt_pk_bf16_f32 v58, v58, v59
	v_mul_f32_e32 v59, v60, v69
	v_mul_f32_e32 v54, v54, v69
	v_mul_f32_e32 v55, v55, v69
	v_mul_f32_e32 v60, v61, v69
	v_cvt_pk_bf16_f32 v59, v59, v60
	global_store_dwordx2 v[64:65], v[58:59], off offset:32
	v_cvt_pk_bf16_f32 v54, v54, v55
	v_mul_f32_e32 v55, v56, v69
	v_mul_f32_e32 v50, v50, v69
	v_mul_f32_e32 v51, v51, v69
	v_mul_f32_e32 v56, v57, v69
	v_cvt_pk_bf16_f32 v55, v55, v56
	global_store_dwordx2 v[64:65], v[54:55], off offset:64
	v_cvt_pk_bf16_f32 v50, v50, v51
	v_mul_f32_e32 v51, v52, v69
	v_mul_f32_e32 v46, v46, v69
	v_mul_f32_e32 v47, v47, v69
	v_mul_f32_e32 v52, v53, v69
	v_cvt_pk_bf16_f32 v51, v51, v52
	global_store_dwordx2 v[64:65], v[50:51], off offset:96
	v_cvt_pk_bf16_f32 v46, v46, v47
	v_mul_f32_e32 v47, v48, v69
	v_mul_f32_e32 v34, v34, v69
	v_mul_f32_e32 v35, v35, v69
	v_mul_f32_e32 v48, v49, v69
	v_cvt_pk_bf16_f32 v47, v47, v48
	global_store_dwordx2 v[64:65], v[46:47], off offset:128
	v_cvt_pk_bf16_f32 v34, v34, v35
	v_mul_f32_e32 v35, v36, v69
	v_mul_f32_e32 v36, v37, v69
	v_cvt_pk_bf16_f32 v35, v35, v36
	global_store_dwordx2 v[64:65], v[34:35], off offset:160
	v_mul_f32_e32 v34, v42, v69
	v_mul_f32_e32 v35, v43, v69
	v_cvt_pk_bf16_f32 v34, v34, v35
	v_mul_f32_e32 v35, v44, v69
	v_mul_f32_e32 v36, v45, v69
	v_cvt_pk_bf16_f32 v35, v35, v36
	s_waitcnt lgkmcnt(0)
	v_add_f32_e32 v0, v166, v0
	global_store_dwordx2 v[64:65], v[34:35], off offset:192
	ds_bpermute_b32 v35, v68, v0
	v_mul_f32_e32 v34, v38, v69
	v_mul_f32_e32 v36, v39, v69
	v_cvt_pk_bf16_f32 v34, v34, v36
	v_mul_f32_e32 v36, v40, v69
	s_waitcnt lgkmcnt(0)
	v_add_f32_e32 v0, v0, v35
	v_div_scale_f32 v37, s[0:1], v0, v0, 1.0
	v_rcp_f32_e32 v38, v37
	v_mul_f32_e32 v35, v41, v69
	v_cvt_pk_bf16_f32 v35, v36, v35
	global_store_dwordx2 v[64:65], v[34:35], off offset:224
	v_fma_f32 v34, -v37, v38, 1.0
	v_fmac_f32_e32 v38, v34, v38
	v_div_scale_f32 v34, vcc, 1.0, v0, 1.0
	v_mul_f32_e32 v35, v34, v38
	v_fma_f32 v36, -v37, v35, v34
	v_fmac_f32_e32 v35, v36, v38
	v_fma_f32 v34, -v37, v35, v34
	v_div_fmas_f32 v34, v34, v38, v35
	v_div_fixup_f32 v0, v34, v0, 1.0
	v_lshlrev_b64 v[34:35], 12, v[162:163]
	v_mul_f32_e32 v30, v30, v0
	v_mul_f32_e32 v31, v31, v0
	v_lshl_add_u64 v[78:79], v[62:63], 0, v[34:35]
	v_cvt_pk_bf16_f32 v30, v30, v31
	v_mul_f32_e32 v31, v32, v0
	v_mul_f32_e32 v26, v26, v0
	v_mul_f32_e32 v27, v27, v0
	v_mul_f32_e32 v32, v33, v0
	v_cvt_pk_bf16_f32 v31, v31, v32
	global_store_dwordx2 v[78:79], v[30:31], off
	v_cvt_pk_bf16_f32 v26, v26, v27
	v_mul_f32_e32 v27, v28, v0
	v_mul_f32_e32 v22, v22, v0
	v_mul_f32_e32 v23, v23, v0
	v_mul_f32_e32 v28, v29, v0
	v_cvt_pk_bf16_f32 v27, v27, v28
	global_store_dwordx2 v[78:79], v[26:27], off offset:32
	v_cvt_pk_bf16_f32 v22, v22, v23
	v_mul_f32_e32 v23, v24, v0
	v_mul_f32_e32 v18, v18, v0
	v_mul_f32_e32 v19, v19, v0
	v_mul_f32_e32 v24, v25, v0
	v_cvt_pk_bf16_f32 v23, v23, v24
	global_store_dwordx2 v[78:79], v[22:23], off offset:64
	v_cvt_pk_bf16_f32 v18, v18, v19
	v_mul_f32_e32 v19, v20, v0
	v_mul_f32_e32 v14, v14, v0
	v_mul_f32_e32 v15, v15, v0
	v_mul_f32_e32 v20, v21, v0
	v_cvt_pk_bf16_f32 v19, v19, v20
	global_store_dwordx2 v[78:79], v[18:19], off offset:96
	v_cvt_pk_bf16_f32 v14, v14, v15
	v_mul_f32_e32 v15, v16, v0
	v_mul_f32_e32 v10, v10, v0
	v_mul_f32_e32 v11, v11, v0
	v_mul_f32_e32 v16, v17, v0
	v_cvt_pk_bf16_f32 v15, v15, v16
	global_store_dwordx2 v[78:79], v[14:15], off offset:128
	v_cvt_pk_bf16_f32 v10, v10, v11
	v_mul_f32_e32 v11, v12, v0
	v_mul_f32_e32 v6, v6, v0
	v_mul_f32_e32 v7, v7, v0
	v_mul_f32_e32 v12, v13, v0
	v_cvt_pk_bf16_f32 v11, v11, v12
	global_store_dwordx2 v[78:79], v[10:11], off offset:160
	v_cvt_pk_bf16_f32 v6, v6, v7
	v_mul_f32_e32 v7, v8, v0
	v_mul_f32_e32 v2, v2, v0
	v_mul_f32_e32 v8, v9, v0
	v_cvt_pk_bf16_f32 v7, v7, v8
	global_store_dwordx2 v[78:79], v[6:7], off offset:192
	v_mul_f32_e32 v3, v3, v0
	v_cvt_pk_bf16_f32 v80, v2, v3
	v_mul_f32_e32 v2, v4, v0
	v_mul_f32_e32 v0, v5, v0
	v_cvt_pk_bf16_f32 v81, v2, v0
	s_cbranch_execnz .LBB0_218

.LBB0_253:
	s_and_b64 s[0:1], exec, s[50:51]
	s_cselect_b32 s28, 0x100, s85
	s_lshl_b32 s0, s11, 10
	s_add_i32 s2, s0, 0xffffd000
	s_lshl_b32 s4, s11, 8
	v_bfe_u32 v79, v77, 7, 1
	s_and_b64 s[0:1], exec, s[50:51]
	v_lshlrev_b32_e32 v102, 3, v79
	s_cselect_b32 s54, s4, s2
	v_xad_u32 v0, v102, -1, s28
	v_cmp_gt_u32_e64 s[4:5], s71, v77
	s_add_i32 s0, s10, 0xa00
	v_mov_b64_e32 v[2:3], s[22:23]
	v_cndmask_b32_e64 v0, v0, v102, s[4:5]
	v_add_u32_e32 v0, s54, v0
	v_or_b32_e32 v78, s0, v74
	v_mad_i64_i32 v[70:71], s[0:1], v0, s72, v[2:3]
	v_or_b32_e32 v118, 1, v102
	v_xad_u32 v0, v102, -2, s28
	v_cndmask_b32_e64 v0, v0, v118, s[4:5]
	v_lshlrev_b32_e32 v80, 1, v78
	v_mov_b32_e32 v81, v1
	v_add_u32_e32 v0, s54, v0
	v_lshl_add_u64 v[82:83], v[70:71], 0, v[80:81]
	v_mad_i64_i32 v[84:85], s[0:1], v0, s72, v[2:3]
	v_lshl_add_u64 v[86:87], v[84:85], 0, v[80:81]
	global_load_ushort v103, v[82:83], off
	global_load_ushort v116, v[86:87], off
	v_or_b32_e32 v0, 2, v102
	v_xad_u32 v82, v102, -3, s28
	v_cndmask_b32_e64 v0, v82, v0, s[4:5]
	v_add_u32_e32 v0, s54, v0
	v_mad_i64_i32 v[82:83], s[0:1], v0, s72, v[2:3]
	v_or_b32_e32 v0, 3, v102
	v_xad_u32 v88, v102, -4, s28
	v_cndmask_b32_e64 v0, v88, v0, s[4:5]
	v_add_u32_e32 v0, s54, v0
	v_mad_i64_i32 v[104:105], s[0:1], v0, s72, v[2:3]
	v_or_b32_e32 v0, 4, v102
	v_xad_u32 v101, v102, -5, s28
	v_cndmask_b32_e64 v0, v101, v0, s[4:5]
	v_add_u32_e32 v0, s54, v0
	v_lshl_add_u64 v[86:87], v[82:83], 0, v[80:81]
	v_mad_i64_i32 v[106:107], s[0:1], v0, s72, v[2:3]
	v_lshl_add_u64 v[88:89], v[104:105], 0, v[80:81]
	v_lshl_add_u64 v[108:109], v[106:107], 0, v[80:81]
	global_load_ushort v117, v[86:87], off
	global_load_ushort v119, v[88:89], off
	global_load_ushort v120, v[108:109], off
	v_or_b32_e32 v0, 5, v102
	v_xad_u32 v86, v102, -6, s28
	v_cndmask_b32_e64 v0, v86, v0, s[4:5]
	v_add_u32_e32 v0, s54, v0
	v_mad_i64_i32 v[86:87], s[0:1], v0, s72, v[2:3]
	v_or_b32_e32 v0, 6, v102
	v_xad_u32 v101, v102, -7, s28
	v_cndmask_b32_e64 v0, v101, v0, s[4:5]
	v_add_u32_e32 v0, s54, v0
	v_mad_i64_i32 v[108:109], s[0:1], v0, s72, v[2:3]
	v_or_b32_e32 v0, 7, v102
	v_xad_u32 v101, v102, -8, s28
	v_cndmask_b32_e64 v0, v101, v0, s[4:5]
	v_add_u32_e32 v0, s54, v0
	v_mad_i64_i32 v[112:113], s[0:1], v0, s72, v[2:3]
	s_add_i32 s0, s10, 0xe00
	v_lshl_add_u64 v[88:89], v[86:87], 0, v[80:81]
	v_lshl_add_u64 v[2:3], v[112:113], 0, v[80:81]
	v_or_b32_e32 v0, s0, v74
	v_lshl_add_u64 v[110:111], v[108:109], 0, v[80:81]
	global_load_ushort v121, v[88:89], off
	global_load_ushort v122, v[110:111], off
	global_load_ushort v123, v[2:3], off
	v_lshl_add_u32 v2, v72, 10, v0
	v_ashrrev_i32_e32 v3, 31, v2
	v_add_u32_e32 v88, s10, v74
	v_lshlrev_b64 v[2:3], 1, v[2:3]
	v_lshlrev_b32_e32 v0, 1, v88
	v_lshl_add_u64 v[80:81], v[86:87], 0, v[0:1]
	v_lshl_add_u64 v[114:115], v[112:113], 0, v[2:3]
	v_lshl_add_u64 v[112:113], v[112:113], 0, v[0:1]
	v_lshl_add_u64 v[110:111], v[108:109], 0, v[2:3]
	v_lshl_add_u64 v[108:109], v[108:109], 0, v[0:1]
	global_load_ushort v89, v[80:81], off offset:3072
	global_load_ushort v135, v[110:111], off
	global_load_ushort v136, v[108:109], off offset:3072
	global_load_ushort v137, v[114:115], off
	global_load_ushort v138, v[112:113], off offset:3072
	s_waitcnt vmcnt(13)
	v_sub_f32_e32 v101, v69, v68
	v_lshl_add_u64 v[68:69], v[70:71], 0, v[2:3]
	v_lshl_add_u64 v[112:113], v[82:83], 0, v[2:3]
	v_lshl_add_u64 v[70:71], v[70:71], 0, v[0:1]
	v_lshl_add_u64 v[80:81], v[84:85], 0, v[2:3]
	v_lshl_add_u64 v[84:85], v[84:85], 0, v[0:1]
	v_lshl_add_u64 v[82:83], v[82:83], 0, v[0:1]
	global_load_ushort v108, v[68:69], off
	global_load_ushort v109, v[70:71], off offset:3072
	global_load_ushort v110, v[80:81], off
	global_load_ushort v111, v[84:85], off offset:3072
	s_nop 0
	global_load_ushort v113, v[112:113], off
	s_nop 0
	global_load_ushort v114, v[82:83], off offset:3072
	v_lshl_add_u64 v[68:69], v[104:105], 0, v[2:3]
	v_lshl_add_u64 v[70:71], v[104:105], 0, v[0:1]
	v_lshl_add_u64 v[80:81], v[106:107], 0, v[2:3]
	v_lshl_add_u64 v[82:83], v[106:107], 0, v[0:1]
	v_lshl_add_u64 v[84:85], v[86:87], 0, v[2:3]
	global_load_ushort v129, v[68:69], off
	global_load_ushort v131, v[70:71], off offset:3072
	global_load_ushort v132, v[80:81], off
	global_load_ushort v133, v[82:83], off offset:3072
	global_load_ushort v134, v[84:85], off
	v_mul_f32_e32 v0, 0x3fb8aa3b, v101
	v_exp_f32_e32 v0, v0
	s_lshr_b32 s37, s28, 4
	s_ashr_i32 s55, s54, 31
	v_mad_i32_i24 v81, v72, s70, 0
	v_add_f32_e32 v0, 1.0, v0
	v_div_scale_f32 v68, s[0:1], v0, v0, 1.0
	v_rcp_f32_e32 v69, v68
	s_lshl_b32 s0, s10, 2
	s_add_u32 s0, s65, s0
	s_addc_u32 s1, s66, 0
	v_fma_f32 v70, -v68, v69, 1.0
	v_fmac_f32_e32 v69, v70, v69
	v_div_scale_f32 v70, vcc, 1.0, v0, 1.0
	v_mul_f32_e32 v71, v70, v69
	v_fma_f32 v80, -v68, v71, v70
	v_fmac_f32_e32 v71, v80, v69
	v_fma_f32 v68, -v68, v71, v70
	v_div_fmas_f32 v68, v68, v69, v71
	v_div_fixup_f32 v80, v68, v0, 1.0
	v_and_b32_e32 v0, 0xff, v77
	s_waitcnt vmcnt(22)
	v_lshl_or_b32 v68, v116, 16, v103
	v_lshl_add_u32 v103, v0, 2, v81
	v_lshlrev_b32_e32 v0, 2, v73
	v_mul_hi_i32_i24_e32 v85, 0x3000, v72
	v_mul_i32_i24_e32 v84, 0x3000, v72
	v_lshl_add_u64 v[72:73], s[0:1], 0, v[0:1]
	v_lshlrev_b32_e32 v0, 2, v75
	v_lshlrev_b32_e32 v112, 3, v91
	v_lshl_add_u64 v[86:87], v[72:73], 0, v[0:1]
	v_mad_u32_u24 v0, v79, s74, v74
	s_waitcnt vmcnt(20)
	v_lshl_or_b32 v69, v119, 16, v117
	v_lshl_add_u32 v104, v74, 2, v81
	v_add_u32_e32 v107, v81, v112
	v_lshl_add_u32 v117, v0, 1, v81
	v_mad_u32_u24 v0, v118, s75, v74
	v_and_b32_e32 v101, 63, v77
	v_sub_f32_e32 v82, 1.0, v80
	v_mad_u32_u24 v77, v74, 28, v104
	v_mul_i32_i24_e32 v128, 0xffffffe4, v74
	v_mad_u32_u24 v83, v75, s73, v81
	v_add_u32_e32 v116, v107, v112
	v_lshl_add_u32 v118, v0, 1, v81
	v_or_b32_e32 v115, 2, v94
	v_or_b32_e32 v112, 3, v94
	v_lshlrev_b32_e32 v126, 5, v75
	v_lshl_add_u32 v72, v76, 10, v107
	s_mov_b32 s53, 0
	v_cmp_eq_u32_e32 vcc, 0, v79
	v_lshl_add_u32 v105, v79, 4, v77
	s_waitcnt vmcnt(18)
	v_lshl_or_b32 v70, v121, 16, v120
	v_lshl_add_u32 v106, v91, 4, v83
	s_waitcnt vmcnt(16)
	v_lshl_or_b32 v71, v123, 16, v122
	v_lshl_add_u64 v[84:85], v[84:85], 0, s[54:55]
	v_add_u32_e32 v119, 0x110, v118
	v_add_u32_e32 v120, 0x220, v118
	v_add_u32_e32 v121, 0x330, v118
	v_add_u32_e32 v122, 0x440, v118
	v_add_u32_e32 v123, 0x550, v118
	v_add_u32_e32 v124, 0x660, v118
	v_lshl_add_u32 v125, v94, 1, v83
	v_cmp_gt_u32_e64 s[6:7], v94, v75
	v_cmp_lt_u32_e64 s[8:9], v94, v75
	v_cmp_gt_u32_e64 s[10:11], v115, v75
	v_cmp_gt_u32_e64 s[12:13], v112, v75
	v_mov_b32_e32 v81, v80
	v_mov_b32_e32 v83, v82
	v_xad_u32 v127, v94, -1, s28
	v_lshlrev_b32_e32 v0, 1, v88
	v_lshlrev_b32_e32 v88, 1, v78
	v_add_u32_e32 v128, v77, v128
	v_add_u32_e32 v130, v72, v126
	s_mov_b32 s0, 0
	v_bfe_u32 v216, v176, 4, 4
	v_lshl_add_u32 v216, s0, 4, v216
	v_xad_u32 v217, v216, -1, s28
	v_cndmask_b32_e64 v216, v217, v216, s[4:5]
	v_add_u32_e32 v216, s54, v216
	v_and_b32_e32 v221, 0x7f, v176
	v_lshlrev_b32_e32 v221, 1, v221
	v_sub_u32_e32 v221, v0, v221
	v_and_b32_e32 v220, 15, v176
	v_lshl_add_u32 v220, v220, 4, v221
	v_add_u32_e32 v220, 0xc00, v220
	v_mad_u32_u24 v220, v216, s72, v220
	v_mov_b32_e32 v221, 0
	v_lshl_add_u64 v[218:219], s[22:23], 0, v[220:221]
	v_mov_b32_e32 v222, 0x1000
	v_mov_b32_e32 v223, 0x1800
	v_cndmask_b32_e64 v222, v223, v222, s[4:5]
	v_mov_b32_e32 v223, 0
	v_lshl_add_u64 v[222:223], v[218:219], 0, v[222:223]
	s_and_b32 s1, s0, 1
	s_mul_i32 s1, s1, 24576
	v_lshrrev_b32_e32 v224, 6, v176
	s_nop 1
	v_readfirstlane_b32 s0, v224
	s_nop 3
	s_mul_i32 s0, s0, 0xc00
	s_add_i32 s1, s1, s0
	s_add_i32 s1, s1, 0xa000
	s_mov_b32 m0, s1
	s_nop 0
	global_load_lds_dwordx4 v[222:223], off
	s_add_i32 m0, s1, 0x400
	s_nop 0
	global_load_lds_dwordx4 v[218:219], off
	s_mov_b32 m0, s1
	s_nop 0
	global_load_lds_dwordx4 v[218:219], off offset:2048
	s_waitcnt vmcnt(0)
	s_barrier
	s_branch .LBB0_255
.LBB0_254:
	s_or_b64 exec, exec, s[56:57]
	s_waitcnt lgkmcnt(0)
	s_barrier
	ds_read_b128 v[206:209], v106 offset:4352
	ds_read_b128 v[222:225], v106
	ds_read_b128 v[210:213], v106 offset:4416
	ds_read_b128 v[68:71], v106 offset:64
	ds_read_b128 v[214:217], v106 offset:4480
	ds_read_b128 v[160:163], v106 offset:128
	ds_read_b128 v[218:221], v106 offset:4544
	ds_read_b128 v[168:171], v106 offset:192
	ds_read2_b64 v[186:189], v125 offset1:4
	ds_read2_b64 v[190:193], v125 offset0:8 offset1:12
	ds_read2_b64 v[194:197], v125 offset0:16 offset1:20
	ds_read2_b64 v[198:201], v125 offset0:24 offset1:28
	v_cvt_pk_bf16_f32 v72, v4, v5
	v_cvt_pk_bf16_f32 v73, v6, v7
	v_cvt_pk_bf16_f32 v74, v12, v13
	v_cvt_pk_bf16_f32 v75, v14, v15
	v_cvt_pk_bf16_f32 v76, v8, v9
	v_cvt_pk_bf16_f32 v77, v10, v11
	v_cvt_pk_bf16_f32 v78, v16, v17
	v_cvt_pk_bf16_f32 v79, v18, v19
	v_mov_b32_e32 v158, v1
	v_mov_b32_e32 v159, v1
	v_cndmask_b32_e64 v180, v127, v94, s[4:5]
	v_xad_u32 v182, v94, -2, s28
	v_add_u32_e32 v183, 1, v94
	v_cndmask_b32_e64 v182, v182, v183, s[4:5]
	v_xad_u32 v184, v94, -3, s28
	v_add_u32_e32 v185, 2, v94
	v_cndmask_b32_e64 v184, v184, v185, s[4:5]
	v_xad_u32 v202, v94, -4, s28
	v_add_u32_e32 v203, 3, v94
	v_cndmask_b32_e64 v202, v202, v203, s[4:5]
	v_ashrrev_i32_e32 v181, 31, v180
	v_lshl_add_u64 v[180:181], v[84:85], 0, v[180:181]
	v_lshlrev_b64 v[180:181], 12, v[180:181]
	v_lshl_add_u64 v[180:181], v[86:87], 0, v[180:181]
	v_ashrrev_i32_e32 v183, 31, v182
	v_lshl_add_u64 v[182:183], v[84:85], 0, v[182:183]
	v_lshlrev_b64 v[182:183], 12, v[182:183]
	v_lshl_add_u64 v[182:183], v[86:87], 0, v[182:183]
	v_ashrrev_i32_e32 v185, 31, v184
	v_lshl_add_u64 v[184:185], v[84:85], 0, v[184:185]
	v_lshlrev_b64 v[184:185], 12, v[184:185]
	v_lshl_add_u64 v[184:185], v[86:87], 0, v[184:185]
	v_ashrrev_i32_e32 v203, 31, v202
	v_lshl_add_u64 v[202:203], v[84:85], 0, v[202:203]
	v_lshlrev_b64 v[202:203], 12, v[202:203]
	v_lshl_add_u64 v[202:203], v[86:87], 0, v[202:203]
	v_add_u32_e32 v94, 16, v94
	v_add_u32_e32 v127, -16, v127
	v_add_u32_e32 v147, v107, v126
	v_add_u32_e32 v147, 0x2200, v147
	v_add_u32_e32 v205, 0x800, v147
	s_waitcnt lgkmcnt(10)
	v_mfma_f32_16x16x32_bf16 v[164:167], v[206:209], v[222:225], 0
	s_waitcnt lgkmcnt(8)
	v_mfma_f32_16x16x32_bf16 v[164:167], v[210:213], v[68:71], v[164:167]
	s_waitcnt lgkmcnt(6)
	v_mfma_f32_16x16x32_bf16 v[164:167], v[214:217], v[160:163], v[164:167]
	s_waitcnt lgkmcnt(4)
	v_mfma_f32_16x16x32_bf16 v[164:167], v[218:221], v[168:171], v[164:167]
	ds_read_b128 v[206:209], v116 offset:16896
	ds_read_b128 v[210:213], v116 offset:16960
	ds_read_b128 v[214:217], v116 offset:17024
	ds_read_b128 v[218:221], v116 offset:17088
	ds_read_b128 v[222:225], v116 offset:17152
	ds_read_b64 v[160:161], v130 offset:12800
	ds_read_b64 v[168:169], v130 offset:13312
	s_waitcnt lgkmcnt(10)
	v_mfma_f32_16x16x32_bf16 v[152:155], v[186:189], v[72:75], 0
	v_mov_b32_e32 v162, v1
	v_mfma_f32_16x16x32_bf16 v[148:151], v[186:189], v[76:79], 0
	v_mov_b32_e32 v163, v1
	v_cvt_pk_bf16_f32 v72, v20, v21
	v_cvt_pk_bf16_f32 v73, v22, v23
	v_cvt_pk_bf16_f32 v74, v28, v29
	v_cvt_pk_bf16_f32 v75, v30, v31
	v_cvt_pk_bf16_f32 v76, v24, v25
	v_cvt_pk_bf16_f32 v77, v26, v27
	v_cvt_pk_bf16_f32 v78, v32, v33
	v_cvt_pk_bf16_f32 v79, v34, v35
	v_mov_b32_e32 v170, v1
	s_waitcnt lgkmcnt(9)
	v_mfma_f32_16x16x32_bf16 v[152:155], v[190:193], v[72:75], v[152:155]
	v_mov_b32_e32 v171, v1
	v_mfma_f32_16x16x32_bf16 v[148:151], v[190:193], v[76:79], v[148:151]
	v_cvt_pk_bf16_f32 v72, v36, v37
	v_cvt_pk_bf16_f32 v73, v38, v39
	v_cvt_pk_bf16_f32 v74, v44, v45
	v_cvt_pk_bf16_f32 v75, v46, v47
	v_cvt_pk_bf16_f32 v76, v40, v41
	v_cvt_pk_bf16_f32 v77, v42, v43
	v_cvt_pk_bf16_f32 v78, v48, v49
	v_cvt_pk_bf16_f32 v79, v50, v51
	s_nop 0
	s_waitcnt lgkmcnt(8)
	v_mfma_f32_16x16x32_bf16 v[152:155], v[194:197], v[72:75], v[152:155]
	s_nop 0
	v_mfma_f32_16x16x32_bf16 v[148:151], v[194:197], v[76:79], v[148:151]
	v_cvt_pk_bf16_f32 v72, v52, v53
	v_cvt_pk_bf16_f32 v73, v54, v55
	v_cvt_pk_bf16_f32 v74, v60, v61
	v_cvt_pk_bf16_f32 v75, v62, v63
	v_cvt_pk_bf16_f32 v76, v56, v57
	v_cvt_pk_bf16_f32 v77, v58, v59
	v_cvt_pk_bf16_f32 v78, v64, v65
	v_cvt_pk_bf16_f32 v79, v66, v67
	s_nop 0
	s_waitcnt lgkmcnt(7)
	v_mfma_f32_16x16x32_bf16 v[152:155], v[198:201], v[72:75], v[152:155]
	s_nop 0
	v_mfma_f32_16x16x32_bf16 v[148:151], v[198:201], v[76:79], v[148:151]
	ds_read2_b64 v[186:189], v147 offset1:64
	ds_read2_b64 v[190:193], v147 offset0:128 offset1:192
	ds_read2_b64 v[194:197], v205 offset1:64
	ds_read2_b64 v[198:201], v205 offset0:128 offset1:192
	v_mov_b32_e32 v147, s29
	v_cndmask_b32_e64 v68, v164, v147, s[6:7]
	v_cndmask_b32_e64 v69, 0, v165, s[8:9]
	v_cndmask_b32_e64 v70, v166, 0, s[10:11]
	v_cndmask_b32_e64 v71, v167, 0, s[12:13]
	v_cndmask_b32_e64 v68, v68, v164, s[8:9]
	v_cvt_pk_bf16_f32 v156, v68, v69
	v_cvt_pk_bf16_f32 v157, v70, v71
	ds_read_b128 v[164:167], v116 offset:17216
	s_waitcnt lgkmcnt(5)
	s_nop 0
	v_mfma_f32_16x16x32_bf16 v[152:155], v[156:159], v[160:163], v[152:155]
	v_mfma_f32_16x16x32_bf16 v[148:151], v[156:159], v[168:171], v[148:151]
	v_pk_mul_f32 v[6:7], v[6:7], v[208:209]
	v_pk_mul_f32 v[4:5], v[4:5], v[206:207]
	v_pk_mul_f32 v[10:11], v[10:11], v[208:209]
	v_pk_mul_f32 v[8:9], v[8:9], v[206:207]
	v_pk_mul_f32 v[14:15], v[14:15], v[212:213]
	v_pk_mul_f32 v[12:13], v[12:13], v[210:211]
	v_pk_mul_f32 v[18:19], v[18:19], v[212:213]
	v_pk_mul_f32 v[16:17], v[16:17], v[210:211]
	global_store_dword v[180:181], v152, off
	global_store_dword v[182:183], v153, off
	global_store_dword v[184:185], v154, off
	global_store_dword v[202:203], v155, off
	global_store_dword v[180:181], v148, off offset:64
	global_store_dword v[182:183], v149, off offset:64
	global_store_dword v[184:185], v150, off offset:64
	global_store_dword v[202:203], v151, off offset:64
	v_mov_b32_e32 v202, v1
	v_mov_b32_e32 v203, v1
	ds_read_b128 v[206:209], v116 offset:17280
	ds_read_b128 v[210:213], v116 offset:17344
	s_waitcnt lgkmcnt(6)
	v_mfma_f32_16x16x32_bf16 v[4:7], v[186:189], v[160:163], v[4:7]
	v_mfma_f32_16x16x32_bf16 v[8:11], v[186:189], v[168:171], v[8:11]
	v_pk_mul_f32 v[22:23], v[22:23], v[216:217]
	v_pk_mul_f32 v[20:21], v[20:21], v[214:215]
	v_pk_mul_f32 v[26:27], v[26:27], v[216:217]
	v_pk_mul_f32 v[24:25], v[24:25], v[214:215]
	s_waitcnt lgkmcnt(5)
	v_mfma_f32_16x16x32_bf16 v[12:15], v[188:191], v[160:163], v[12:15]
	v_mfma_f32_16x16x32_bf16 v[16:19], v[188:191], v[168:171], v[16:19]
	v_pk_mul_f32 v[30:31], v[30:31], v[220:221]
	v_pk_mul_f32 v[28:29], v[28:29], v[218:219]
	v_pk_mul_f32 v[34:35], v[34:35], v[220:221]
	v_pk_mul_f32 v[32:33], v[32:33], v[218:219]
	v_mfma_f32_16x16x32_bf16 v[20:23], v[190:193], v[160:163], v[20:23]
	v_mfma_f32_16x16x32_bf16 v[24:27], v[190:193], v[168:171], v[24:27]
	v_pk_mul_f32 v[38:39], v[38:39], v[224:225]
	v_pk_mul_f32 v[36:37], v[36:37], v[222:223]
	v_pk_mul_f32 v[42:43], v[42:43], v[224:225]
	v_pk_mul_f32 v[40:41], v[40:41], v[222:223]
	s_waitcnt lgkmcnt(4)
	v_mfma_f32_16x16x32_bf16 v[28:31], v[192:195], v[160:163], v[28:31]
	v_mfma_f32_16x16x32_bf16 v[32:35], v[192:195], v[168:171], v[32:35]
	s_waitcnt lgkmcnt(2)
	v_pk_mul_f32 v[46:47], v[46:47], v[166:167]
	v_pk_mul_f32 v[44:45], v[44:45], v[164:165]
	v_pk_mul_f32 v[50:51], v[50:51], v[166:167]
	v_pk_mul_f32 v[48:49], v[48:49], v[164:165]
	v_mfma_f32_16x16x32_bf16 v[36:39], v[194:197], v[160:163], v[36:39]
	v_mfma_f32_16x16x32_bf16 v[40:43], v[194:197], v[168:171], v[40:43]
	s_waitcnt lgkmcnt(1)
	v_pk_mul_f32 v[54:55], v[54:55], v[208:209]
	v_pk_mul_f32 v[52:53], v[52:53], v[206:207]
	v_pk_mul_f32 v[58:59], v[58:59], v[208:209]
	v_pk_mul_f32 v[56:57], v[56:57], v[206:207]
	v_mfma_f32_16x16x32_bf16 v[44:47], v[196:199], v[160:163], v[44:47]
	v_mfma_f32_16x16x32_bf16 v[48:51], v[196:199], v[168:171], v[48:51]
	s_waitcnt lgkmcnt(0)
	v_pk_mul_f32 v[62:63], v[62:63], v[212:213]
	v_pk_mul_f32 v[60:61], v[60:61], v[210:211]
	v_pk_mul_f32 v[66:67], v[66:67], v[212:213]
	v_pk_mul_f32 v[64:65], v[64:65], v[210:211]
	v_mfma_f32_16x16x32_bf16 v[52:55], v[198:201], v[160:163], v[52:55]
	v_mfma_f32_16x16x32_bf16 v[56:59], v[198:201], v[168:171], v[56:59]
	v_mfma_f32_16x16x32_bf16 v[60:63], v[200:203], v[160:163], v[60:63]
	v_mfma_f32_16x16x32_bf16 v[64:67], v[200:203], v[168:171], v[64:67]
	s_waitcnt vmcnt(8)
	s_cmp_eq_u32 s37, s53
	s_waitcnt lgkmcnt(0)
	s_barrier
	s_cbranch_scc1 .LBB0_257
.LBB0_255:
	s_mov_b32 s0, s53
	s_add_i32 s53, s53, 1
	s_cmp_lt_u32 s53, s37
	s_cselect_b32 s0, s53, s0
	s_and_b32 s1, s53, 1
	s_xor_b32 s1, s1, 1
	s_mul_i32 s1, s1, 24576
	v_lshrrev_b32_e32 v206, 7, v176
	v_mul_u32_u24_e32 v206, 0x1800, v206
	v_and_b32_e32 v207, 0x7f, v176
	v_lshl_add_u32 v207, v207, 1, v206
	v_add_u32_e32 v207, s1, v207
	v_add_u32_e32 v207, 0xa000, v207
	ds_read_u16 v108, v207 offset:0
	ds_read_u16 v109, v207 offset:1024
	ds_read_u16 v110, v207 offset:256
	ds_read_u16 v111, v207 offset:1280
	ds_read_u16 v113, v207 offset:512
	ds_read_u16 v114, v207 offset:1536
	ds_read_u16 v129, v207 offset:768
	ds_read_u16 v131, v207 offset:1792
	ds_read_u16 v132, v207 offset:3072
	ds_read_u16 v133, v207 offset:4096
	ds_read_u16 v134, v207 offset:3328
	ds_read_u16 v89, v207 offset:4352
	s_waitcnt lgkmcnt(6)
	ds_read_u16 v135, v207 offset:3584
	ds_read_u16 v136, v207 offset:4608
	ds_read_u16 v137, v207 offset:3840
	ds_read_u16 v138, v207 offset:4864
	ds_read_u16 v208, v207 offset:2048
	ds_read_u16 v209, v207 offset:2304
	ds_read_u16 v210, v207 offset:2560
	ds_read_u16 v211, v207 offset:2816
	ds_read_u16 v212, v207 offset:5120
	ds_read_u16 v213, v207 offset:5376
	ds_read_u16 v214, v207 offset:5632
	ds_read_u16 v215, v207 offset:5888
	v_bfe_u32 v216, v176, 4, 4
	v_lshl_add_u32 v216, s0, 4, v216
	v_xad_u32 v217, v216, -1, s28
	v_cndmask_b32_e64 v216, v217, v216, s[4:5]
	v_add_u32_e32 v216, s54, v216
	v_and_b32_e32 v221, 0x7f, v176
	v_lshlrev_b32_e32 v221, 1, v221
	v_sub_u32_e32 v221, v0, v221
	v_and_b32_e32 v220, 15, v176
	v_lshl_add_u32 v220, v220, 4, v221
	v_add_u32_e32 v220, 0xc00, v220
	v_mad_u32_u24 v220, v216, s72, v220
	v_mov_b32_e32 v221, 0
	v_lshl_add_u64 v[218:219], s[22:23], 0, v[220:221]
	v_mov_b32_e32 v222, 0x1000
	v_mov_b32_e32 v223, 0x1800
	v_cndmask_b32_e64 v222, v223, v222, s[4:5]
	v_mov_b32_e32 v223, 0
	v_lshl_add_u64 v[222:223], v[218:219], 0, v[222:223]
	s_and_b32 s1, s0, 1
	s_mul_i32 s1, s1, 24576
	v_lshrrev_b32_e32 v224, 6, v176
	s_nop 1
	v_readfirstlane_b32 s0, v224
	s_nop 3
	s_mul_i32 s0, s0, 0xc00
	s_add_i32 s1, s1, s0
	s_add_i32 s1, s1, 0xa000
	s_cmp_lt_u32 s53, s37
	s_cbranch_scc0 .Lhg_skip_dma
	s_mov_b32 m0, s1
	s_nop 0
	global_load_lds_dwordx4 v[222:223], off
	s_add_i32 m0, s1, 0x400
	s_nop 0
	global_load_lds_dwordx4 v[218:219], off
	s_mov_b32 m0, s1
	s_nop 0
	global_load_lds_dwordx4 v[218:219], off offset:2048
.Lhg_skip_dma:
	s_waitcnt lgkmcnt(0)
	v_lshlrev_b32_e32 v169, 16, v138
	v_lshlrev_b32_e32 v143, 16, v108
	v_lshlrev_b32_e32 v156, 16, v109
	v_lshlrev_b32_e32 v165, 16, v89
	v_lshlrev_b32_e32 v154, 16, v110
	v_lshlrev_b32_e32 v157, 16, v111
	v_lshlrev_b32_e32 v162, 16, v132
	v_lshlrev_b32_e32 v163, 16, v133
	v_lshlrev_b32_e32 v164, 16, v134
	v_lshlrev_b32_e32 v166, 16, v135
	v_lshlrev_b32_e32 v160, 16, v129
	v_lshlrev_b32_e32 v161, 16, v131
	v_lshlrev_b32_e32 v167, 16, v136
	v_lshlrev_b32_e32 v168, 16, v137
	v_lshlrev_b32_e32 v158, 16, v113
	v_lshlrev_b32_e32 v159, 16, v114
	v_lshl_or_b32 v68, v209, 16, v208
	v_lshl_or_b32 v69, v211, 16, v210
	v_lshl_or_b32 v70, v213, 16, v212
	v_lshl_or_b32 v71, v215, 16, v214
	v_mul_f32_e32 v135, 0xbfb8aa3b, v143
	v_exp_f32_e32 v135, v135
	v_mul_f32_e32 v138, 0xbfb8aa3b, v154
	v_exp_f32_e32 v138, v138
	v_add_f32_e32 v89, 1.0, v135
	v_rcp_f32_e32 v154, v89
	v_add_f32_e32 v89, 1.0, v138
	v_rcp_f32_e32 v155, v89
	v_mul_f32_e32 v72, 0xbfb8aa3b, v158
	v_exp_f32_e32 v74, v72
	v_mul_f32_e32 v75, 0xbfb8aa3b, v160
	v_exp_f32_e32 v75, v75
	v_pk_fma_f32 v[72:73], v[82:83], v[154:155], v[80:81]
	v_add_f32_e32 v74, 1.0, v74
	v_rcp_f32_e32 v74, v74
	v_sub_f32_e32 v77, 1.0, v73
	v_mul_f32_e32 v78, v72, v73
	v_mul_f32_e32 v151, 0xbfb8aa3b, v168
	v_fma_f32 v73, v82, v74, v80
	v_add_f32_e32 v74, 1.0, v75
	v_mul_f32_e32 v75, 0xbfb8aa3b, v162
	v_rcp_f32_e32 v74, v74
	v_exp_f32_e32 v75, v75
	v_sub_f32_e32 v79, 1.0, v73
	v_mul_f32_e32 v147, v78, v73
	v_fma_f32 v73, v82, v74, v80
	v_add_f32_e32 v74, 1.0, v75
	v_mul_f32_e32 v75, 0xbfb8aa3b, v164
	v_rcp_f32_e32 v74, v74
	v_exp_f32_e32 v75, v75
	v_sub_f32_e32 v148, 1.0, v73
	v_mul_f32_e32 v149, v147, v73
	v_fma_f32 v73, v82, v74, v80
	v_add_f32_e32 v74, 1.0, v75
	v_mul_f32_e32 v75, 0xbfb8aa3b, v166
	v_rcp_f32_e32 v74, v74
	v_exp_f32_e32 v75, v75
	v_exp_f32_e32 v151, v151
	v_mul_f32_e32 v150, v149, v73
	v_fma_f32 v152, v82, v74, v80
	v_add_f32_e32 v74, 1.0, v75
	v_rcp_f32_e32 v74, v74
	v_add_f32_e32 v75, 1.0, v151
	v_rcp_f32_e32 v75, v75
	v_mul_f32_e32 v151, v150, v152
	v_fma_f32 v153, v82, v74, v80
	v_mul_f32_e32 v154, v151, v153
	v_fma_f32 v155, v82, v75, v80
	v_mul_f32_e32 v158, v154, v155
	ds_write_b32 v103, v158 offset:17408
	s_waitcnt lgkmcnt(0)
	s_barrier
	ds_read2st64_b32 v[74:75], v104 offset0:68 offset1:70
	v_sub_f32_e32 v160, 1.0, v73
	v_sub_f32_e32 v73, 1.0, v153
	v_sub_f32_e32 v153, 1.0, v155
	v_sub_f32_e32 v76, 1.0, v72
	s_waitcnt lgkmcnt(0)
	v_cndmask_b32_e64 v155, v74, 1.0, vcc
	v_mul_f32_e32 v72, v72, v155
	v_rcp_f32_e32 v162, v72
	v_mul_f32_e32 v156, 0x3db504f3, v156
	v_mul_f32_e32 v72, v156, v72
	v_cvt_pk_bf16_f32 v72, v72, v1
	ds_write_b16 v117, v72
	v_mul_f32_e32 v156, v76, v162
	v_cvt_pk_bf16_f32 v72, v156, v1
	ds_write_b16 v117, v72 offset:4352
	v_mul_f32_e32 v72, v78, v155
	v_rcp_f32_e32 v76, v72
	v_mul_f32_e32 v78, 0x3db504f3, v157
	v_mul_f32_e32 v72, v78, v72
	v_cvt_pk_bf16_f32 v72, v72, v1
	ds_write_b16 v118, v72
	v_mul_f32_e32 v78, v77, v76
	v_cvt_pk_bf16_f32 v72, v78, v1
	ds_write_b16 v118, v72 offset:4352
	v_mul_f32_e32 v72, v147, v155
	v_rcp_f32_e32 v76, v72
	v_mul_f32_e32 v77, 0x3db504f3, v159
	v_mul_f32_e32 v72, v77, v72
	v_cvt_pk_bf16_f32 v72, v72, v1
	ds_write_b16 v119, v72
	v_mul_f32_e32 v79, v79, v76
	v_cvt_pk_bf16_f32 v72, v79, v1
	ds_write_b16 v119, v72 offset:4352
	v_mul_f32_e32 v72, v149, v155
	v_rcp_f32_e32 v76, v72
	v_mul_f32_e32 v77, 0x3db504f3, v161
	v_mul_f32_e32 v72, v77, v72
	v_cvt_pk_bf16_f32 v72, v72, v1
	ds_write_b16 v120, v72
	v_mul_f32_e32 v147, v148, v76
	v_cvt_pk_bf16_f32 v72, v147, v1
	ds_write_b16 v120, v72 offset:4352
	v_mul_f32_e32 v72, v150, v155
	v_rcp_f32_e32 v76, v72
	v_mul_f32_e32 v77, 0x3db504f3, v163
	v_mul_f32_e32 v72, v77, v72
	v_cvt_pk_bf16_f32 v72, v72, v1
	ds_write_b16 v121, v72
	v_mul_f32_e32 v148, v160, v76
	v_cvt_pk_bf16_f32 v72, v148, v1
	ds_write_b16 v121, v72 offset:4352
	v_mul_f32_e32 v72, v151, v155
	v_rcp_f32_e32 v76, v72
	v_mul_f32_e32 v77, 0x3db504f3, v165
	v_mul_f32_e32 v72, v77, v72
	v_sub_f32_e32 v152, 1.0, v152
	v_cvt_pk_bf16_f32 v72, v72, v1
	ds_write_b16 v122, v72
	v_mul_f32_e32 v149, v152, v76
	v_cvt_pk_bf16_f32 v72, v149, v1
	ds_write_b16 v122, v72 offset:4352
	v_mul_f32_e32 v72, v154, v155
	v_rcp_f32_e32 v77, v72
	v_mul_f32_e32 v76, 0x3db504f3, v167
	v_mul_f32_e32 v72, v76, v72
	v_cvt_pk_bf16_f32 v72, v72, v1
	ds_write_b16 v123, v72
	v_mov_b32_e32 v72, v74
	v_mov_b32_e32 v76, v75
	v_pk_mul_f32 v[72:73], v[72:73], v[76:77]
	s_nop 0
	v_mul_f32_e32 v77, v72, v147
	v_cvt_pk_bf16_f32 v147, v73, v1
	ds_write_b16 v123, v147 offset:4352
	v_mul_f32_e32 v147, v158, v155
	v_mul_f32_e32 v75, v72, v78
	v_mul_f32_e32 v78, v72, v148
	v_rcp_f32_e32 v148, v147
	v_mul_f32_e32 v76, v72, v79
	v_mul_f32_e32 v79, v72, v149
	v_mul_f32_e32 v149, 0x3db504f3, v169
	v_mul_f32_e32 v147, v149, v147
	v_cvt_pk_bf16_f32 v147, v147, v1
	v_mul_f32_e32 v74, v72, v156
	ds_write_b16 v124, v147
	v_mul_f32_e32 v147, v153, v148
	v_mul_f32_e32 v73, v72, v73
	v_cvt_pk_bf16_f32 v148, v147, v1
	ds_write_b16 v124, v148 offset:4352
	v_mul_f32_e32 v147, v72, v147
	v_cvt_pk_bf16_f32 v74, v74, v75
	v_cvt_pk_bf16_f32 v75, v76, v77
	v_cvt_pk_bf16_f32 v76, v78, v79
	v_cvt_pk_bf16_f32 v77, v73, v147
	ds_write_b128 v105, v[74:77] offset:8704
	ds_write_b128 v105, v[68:71] offset:12800
	s_and_saveexec_b64 s[56:57], vcc
	s_cbranch_execz .LBB0_254
	ds_write_b32 v128, v72 offset:16896
	s_branch .LBB0_254

.LBB0_262:
	s_mov_b64 s[50:51], 0
	s_and_b64 vcc, exec, s[4:5]
	s_cbranch_vccz .LBB0_211
	v_mov_b32_e32 v3, v176
	s_lshl_b32 s0, s56, 7
	s_and_b32 s0, s0, 0x380
	v_and_b32_e32 v28, 0x7f, v3
	v_or_b32_e32 v2, s0, v28
	v_lshlrev_b32_e32 v0, 2, v2
	v_lshl_add_u64 v[4:5], s[16:17], 0, v[0:1]
	v_add_co_u32_e32 v4, vcc, s69, v4
	global_load_dword v29, v0, s[16:17]
	s_nop 0
	v_addc_co_u32_e32 v5, vcc, 0, v5, vcc
	global_load_dword v5, v[4:5], off
	v_bfe_u32 v30, v3, 7, 1
	s_add_i32 s28, s56, 0xfffffec0
	v_lshlrev_b32_e32 v96, 3, v30
	s_lshl_b32 s1, s28, 5
	v_xor_b32_e32 v0, 0xff, v96
	v_cmp_gt_u32_e64 s[4:5], s71, v3
	s_and_b32 s52, s1, 0x7fffff00
	v_mov_b64_e32 v[6:7], s[22:23]
	v_cndmask_b32_e64 v0, v0, v96, s[4:5]
	v_or_b32_e32 v0, s52, v0
	s_add_i32 s1, s0, 0xa00
	v_mad_u64_u32 v[8:9], s[6:7], v0, s72, v[6:7]
	v_or_b32_e32 v31, 1, v96
	v_xad_u32 v0, v96, -2, v177
	v_or_b32_e32 v4, s1, v28
	v_cndmask_b32_e64 v0, v0, v31, s[4:5]
	v_lshlrev_b32_e32 v10, 1, v4
	v_mov_b32_e32 v11, v1
	v_or_b32_e32 v0, s52, v0
	v_lshl_add_u64 v[12:13], v[8:9], 0, v[10:11]
	v_mad_u64_u32 v[14:15], s[6:7], v0, s72, v[6:7]
	v_lshl_add_u64 v[16:17], v[14:15], 0, v[10:11]
	global_load_ushort v32, v[12:13], off
	global_load_ushort v33, v[16:17], off
	v_or_b32_e32 v0, 2, v96
	v_xad_u32 v12, v96, -3, v177
	v_cndmask_b32_e64 v0, v12, v0, s[4:5]
	v_or_b32_e32 v0, s52, v0
	v_mad_u64_u32 v[12:13], s[6:7], v0, s72, v[6:7]
	v_or_b32_e32 v0, 3, v96
	v_xad_u32 v18, v96, -4, v177
	v_cndmask_b32_e64 v0, v18, v0, s[4:5]
	v_or_b32_e32 v0, s52, v0
	v_mad_u64_u32 v[18:19], s[6:7], v0, s72, v[6:7]
	v_or_b32_e32 v0, 4, v96
	v_xad_u32 v22, v96, -5, v177
	v_cndmask_b32_e64 v0, v22, v0, s[4:5]
	v_or_b32_e32 v0, s52, v0
	v_lshl_add_u64 v[16:17], v[12:13], 0, v[10:11]
	v_mad_u64_u32 v[22:23], s[6:7], v0, s72, v[6:7]
	v_lshl_add_u64 v[20:21], v[18:19], 0, v[10:11]
	v_lshl_add_u64 v[24:25], v[22:23], 0, v[10:11]
	global_load_ushort v34, v[16:17], off
	global_load_ushort v35, v[20:21], off
	global_load_ushort v36, v[24:25], off
	v_or_b32_e32 v0, 5, v96
	v_xad_u32 v16, v96, -6, v177
	v_cndmask_b32_e64 v0, v16, v0, s[4:5]
	v_or_b32_e32 v0, s52, v0
	v_mad_u64_u32 v[16:17], s[6:7], v0, s72, v[6:7]
	v_or_b32_e32 v0, 6, v96
	v_xad_u32 v24, v96, -7, v177
	v_cndmask_b32_e64 v0, v24, v0, s[4:5]
	v_or_b32_e32 v0, s52, v0
	v_mad_u64_u32 v[24:25], s[6:7], v0, s72, v[6:7]
	v_or_b32_e32 v0, 7, v96
	v_xad_u32 v37, v96, -8, v177
	v_cndmask_b32_e64 v0, v37, v0, s[4:5]
	v_or_b32_e32 v0, s52, v0
	v_mad_u64_u32 v[6:7], s[6:7], v0, s72, v[6:7]
	s_add_i32 s1, s0, 0xe00
	v_lshl_add_u64 v[20:21], v[16:17], 0, v[10:11]
	v_lshl_add_u64 v[26:27], v[24:25], 0, v[10:11]
	v_lshl_add_u64 v[10:11], v[6:7], 0, v[10:11]
	v_ashrrev_i32_e32 v40, 8, v3
	v_or_b32_e32 v0, s1, v28
	global_load_ushort v37, v[20:21], off
	global_load_ushort v38, v[26:27], off
	global_load_ushort v39, v[10:11], off
	v_lshl_add_u32 v10, v40, 10, v0
	v_ashrrev_i32_e32 v11, 31, v10
	v_lshlrev_b64 v[82:83], 1, v[10:11]
	v_lshlrev_b32_e32 v0, 1, v2
	v_lshl_add_u64 v[10:11], v[16:17], 0, v[0:1]
	v_lshl_add_u64 v[26:27], v[6:7], 0, v[82:83]
	v_lshl_add_u64 v[6:7], v[6:7], 0, v[0:1]
	s_waitcnt vmcnt(8)
	v_sub_f32_e32 v5, v5, v29
	v_mul_f32_e32 v5, 0x3fb8aa3b, v5
	v_exp_f32_e32 v5, v5
	v_lshl_add_u64 v[20:21], v[24:25], 0, v[82:83]
	v_lshl_add_u64 v[24:25], v[24:25], 0, v[0:1]
	global_load_ushort v93, v[10:11], off offset:3072
	global_load_ushort v128, v[20:21], off
	global_load_ushort v129, v[24:25], off offset:3072
	global_load_ushort v130, v[26:27], off
	global_load_ushort v131, v[6:7], off offset:3072
	v_add_f32_e32 v5, 1.0, v5
	v_div_scale_f32 v6, s[6:7], v5, v5, 1.0
	v_rcp_f32_e32 v7, v6
	v_ashrrev_i32_e32 v95, 6, v3
	v_and_b32_e32 v98, 15, v3
	v_mad_i32_i24 v24, v40, s70, 0
	v_fma_f32 v10, -v6, v7, 1.0
	v_fmac_f32_e32 v7, v10, v7
	v_div_scale_f32 v10, vcc, 1.0, v5, 1.0
	v_mul_f32_e32 v11, v10, v7
	v_fma_f32 v20, -v6, v11, v10
	v_fmac_f32_e32 v11, v20, v7
	v_fma_f32 v6, -v6, v11, v10
	v_div_fmas_f32 v6, v6, v7, v11
	v_div_fixup_f32 v84, v6, v5, 1.0
	v_lshl_add_u64 v[6:7], v[8:9], 0, v[82:83]
	v_lshl_add_u64 v[8:9], v[8:9], 0, v[0:1]
	v_lshl_add_u64 v[10:11], v[14:15], 0, v[82:83]
	v_lshl_add_u64 v[14:15], v[14:15], 0, v[0:1]
	v_lshl_add_u64 v[20:21], v[12:13], 0, v[82:83]
	v_lshl_add_u64 v[12:13], v[12:13], 0, v[0:1]
	global_load_ushort v109, v[6:7], off
	global_load_ushort v111, v[8:9], off offset:3072
	global_load_ushort v113, v[10:11], off
	global_load_ushort v115, v[14:15], off offset:3072
	global_load_ushort v118, v[20:21], off
	global_load_ushort v120, v[12:13], off offset:3072
	v_lshl_add_u64 v[6:7], v[18:19], 0, v[82:83]
	v_lshl_add_u64 v[8:9], v[18:19], 0, v[0:1]
	v_lshl_add_u64 v[10:11], v[22:23], 0, v[82:83]
	v_lshl_add_u64 v[12:13], v[22:23], 0, v[0:1]
	v_lshl_add_u64 v[14:15], v[16:17], 0, v[82:83]
	global_load_ushort v132, v[6:7], off
	global_load_ushort v133, v[8:9], off offset:3072
	global_load_ushort v134, v[10:11], off
	global_load_ushort v135, v[12:13], off offset:3072
	global_load_ushort v136, v[14:15], off
	v_and_b32_e32 v0, 0xff, v3
	s_lshl_b32 s0, s0, 2
	v_and_b32_e32 v25, 3, v95
	v_lshl_add_u32 v101, v0, 2, v24
	v_mad_u32_u24 v9, v98, s73, v24
	v_and_b32_e32 v0, 48, v3
	s_add_u32 s0, s65, s0
	v_add_u32_e32 v104, v9, v0
	v_mul_hi_i32_i24_e32 v7, 0x3000, v40
	v_mul_i32_i24_e32 v6, 0x3000, v40
	s_mov_b32 s53, s29
	s_addc_u32 s1, s66, 0
	v_lshlrev_b32_e32 v0, 7, v25
	v_bfe_u32 v97, v3, 4, 2
	v_lshl_add_u64 v[88:89], v[6:7], 0, s[52:53]
	v_lshl_add_u64 v[6:7], s[0:1], 0, v[0:1]
	v_lshlrev_b32_e32 v0, 2, v98
	v_lshlrev_b32_e32 v10, 3, v97
	v_lshl_add_u64 v[90:91], v[6:7], 0, v[0:1]
	v_mad_u32_u24 v0, v30, s74, v28
	v_lshlrev_b32_e32 v100, 2, v97
	v_lshl_add_u32 v102, v28, 2, v24
	v_add_u32_e32 v105, v24, v10
	v_lshl_add_u32 v110, v0, 1, v24
	v_mad_u32_u24 v0, v31, s75, v28
	v_and_b32_e32 v94, 63, v3
	v_sub_f32_e32 v86, 1.0, v84
	v_mad_u32_u24 v5, v28, 28, v102
	v_mul_i32_i24_e32 v8, 0xffffffe4, v28
	v_lshl_add_u32 v112, v0, 1, v24
	v_or_b32_e32 v107, 2, v100
	v_or_b32_e32 v106, 3, v100
	v_lshlrev_b32_e32 v124, 5, v98
	v_lshl_add_u32 v3, v25, 10, v105
	v_mov_b32_e32 v50, 0
	s_mov_b32 s36, 0
	v_lshlrev_b32_e32 v99, 5, v25
	s_waitcnt vmcnt(22)
	v_lshl_or_b32 v66, v33, 16, v32
	s_waitcnt vmcnt(20)
	v_lshl_or_b32 v67, v35, 16, v34
	s_waitcnt vmcnt(18)
	v_lshl_or_b32 v68, v37, 16, v36
	s_waitcnt vmcnt(16)
	v_lshl_or_b32 v69, v39, 16, v38
	v_cmp_eq_u32_e32 vcc, 0, v30
	v_lshl_add_u32 v103, v30, 4, v5
	v_add_u32_e32 v108, v105, v10
	v_add_u32_e32 v114, 0x110, v112
	v_add_u32_e32 v116, 0x220, v112
	v_add_u32_e32 v117, 0x330, v112
	v_add_u32_e32 v119, 0x440, v112
	v_add_u32_e32 v121, 0x550, v112
	v_add_u32_e32 v122, 0x660, v112
	v_add_u32_e32 v123, v9, v10
	v_cmp_gt_u32_e64 s[6:7], v100, v98
	v_cmp_lt_u32_e64 s[8:9], v100, v98
	v_cmp_gt_u32_e64 s[10:11], v107, v98
	v_cmp_gt_u32_e64 s[12:13], v106, v98
	v_mov_b32_e32 v85, v84
	v_mov_b32_e32 v87, v86
	v_xor_b32_e32 v125, 0xff, v100
	v_lshlrev_b32_e32 v0, 1, v2
	v_lshlrev_b32_e32 v92, 1, v4
	v_add_u32_e32 v126, v5, v8
	v_add_u32_e32 v127, v3, v124
	v_mov_b32_e32 v51, v50
	v_mov_b32_e32 v52, v50
	v_mov_b32_e32 v53, v50
	v_mov_b32_e32 v62, v50
	v_mov_b32_e32 v63, v50
	v_mov_b32_e32 v64, v50
	v_mov_b32_e32 v65, v50
	v_mov_b32_e32 v54, v50
	v_mov_b32_e32 v55, v50
	v_mov_b32_e32 v56, v50
	v_mov_b32_e32 v57, v50
	v_mov_b32_e32 v58, v50
	v_mov_b32_e32 v59, v50
	v_mov_b32_e32 v60, v50
	v_mov_b32_e32 v61, v50
	v_mov_b32_e32 v42, v50
	v_mov_b32_e32 v43, v50
	v_mov_b32_e32 v44, v50
	v_mov_b32_e32 v45, v50
	v_mov_b32_e32 v46, v50
	v_mov_b32_e32 v47, v50
	v_mov_b32_e32 v48, v50
	v_mov_b32_e32 v49, v50
	v_mov_b32_e32 v34, v50
	v_mov_b32_e32 v35, v50
	v_mov_b32_e32 v36, v50
	v_mov_b32_e32 v37, v50
	v_mov_b32_e32 v38, v50
	v_mov_b32_e32 v39, v50
	v_mov_b32_e32 v40, v50
	v_mov_b32_e32 v41, v50
	v_mov_b32_e32 v26, v50
	v_mov_b32_e32 v27, v50
	v_mov_b32_e32 v28, v50
	v_mov_b32_e32 v29, v50
	v_mov_b32_e32 v30, v50
	v_mov_b32_e32 v31, v50
	v_mov_b32_e32 v32, v50
	v_mov_b32_e32 v33, v50
	v_mov_b32_e32 v18, v50
	v_mov_b32_e32 v19, v50
	v_mov_b32_e32 v20, v50
	v_mov_b32_e32 v21, v50
	v_mov_b32_e32 v22, v50
	v_mov_b32_e32 v23, v50
	v_mov_b32_e32 v24, v50
	v_mov_b32_e32 v25, v50
	v_mov_b32_e32 v10, v50
	v_mov_b32_e32 v11, v50
	v_mov_b32_e32 v12, v50
	v_mov_b32_e32 v13, v50
	v_mov_b32_e32 v14, v50
	v_mov_b32_e32 v15, v50
	v_mov_b32_e32 v16, v50
	v_mov_b32_e32 v17, v50
	v_mov_b32_e32 v2, v50
	v_mov_b32_e32 v3, v50
	v_mov_b32_e32 v4, v50
	v_mov_b32_e32 v5, v50
	v_mov_b32_e32 v6, v50
	v_mov_b32_e32 v7, v50
	v_mov_b32_e32 v8, v50
	v_mov_b32_e32 v9, v50
	s_waitcnt vmcnt(0)
	s_branch .LBB0_265

.LBB0_265:
	s_mov_b32 s0, s36
	s_add_i32 s36, s36, 1
	s_cmp_lt_u32 s0, 15
	s_cselect_b32 s0, s36, s0
	v_lshl_or_b32 v151, s0, 4, v96
	v_lshlrev_b32_e32 v141, 16, v109
	v_lshlrev_b32_e32 v152, 16, v111
	v_sub_u32_e32 v70, 0xff, v151
	v_or_b32_e32 v109, 1, v151
	v_xad_u32 v111, v151, -2, v177
	v_cndmask_b32_e64 v70, v70, v151, s[4:5]
	v_cndmask_b32_e64 v109, v111, v109, s[4:5]
	v_add_u32_e32 v72, s52, v70
	v_mov_b64_e32 v[70:71], s[22:23]
	v_add_u32_e32 v109, s52, v109
	v_lshlrev_b32_e32 v162, 16, v128
	v_lshlrev_b32_e32 v163, 16, v129
	v_mad_i64_i32 v[128:129], s[0:1], v109, s72, v[70:71]
	v_or_b32_e32 v109, 2, v151
	v_xad_u32 v111, v151, -3, v177
	v_cndmask_b32_e64 v109, v111, v109, s[4:5]
	v_mad_i64_i32 v[72:73], s[0:1], v72, s72, v[70:71]
	v_add_u32_e32 v109, s52, v109
	v_lshlrev_b32_e32 v158, 16, v134
	v_lshlrev_b32_e32 v159, 16, v135
	v_lshlrev_b32_e32 v161, 16, v93
	v_lshlrev_b32_e32 v164, 16, v130
	v_lshlrev_b32_e32 v165, 16, v131
	v_lshl_add_u64 v[74:75], v[72:73], 0, v[82:83]
	v_mov_b32_e32 v93, v1
	v_lshl_add_u64 v[130:131], v[128:129], 0, v[82:83]
	v_mad_i64_i32 v[134:135], s[0:1], v109, s72, v[70:71]
	v_lshlrev_b32_e32 v150, 16, v113
	v_lshlrev_b32_e32 v153, 16, v115
	v_lshlrev_b32_e32 v154, 16, v118
	v_lshlrev_b32_e32 v155, 16, v120
	v_lshlrev_b32_e32 v156, 16, v132
	v_lshlrev_b32_e32 v157, 16, v133
	v_lshl_add_u64 v[76:77], v[72:73], 0, v[0:1]
	v_lshl_add_u64 v[72:73], v[72:73], 0, v[92:93]
	v_lshl_add_u64 v[132:133], v[128:129], 0, v[0:1]
	v_lshl_add_u64 v[128:129], v[128:129], 0, v[92:93]
	v_lshl_add_u64 v[138:139], v[134:135], 0, v[82:83]
	v_lshl_add_u64 v[142:143], v[134:135], 0, v[0:1]
	global_load_ushort v109, v[74:75], off
	global_load_ushort v111, v[76:77], off offset:3072
	global_load_ushort v137, v[72:73], off
	global_load_ushort v113, v[130:131], off
	global_load_ushort v115, v[132:133], off offset:3072
	global_load_ushort v140, v[128:129], off
	global_load_ushort v118, v[138:139], off
	global_load_ushort v120, v[142:143], off offset:3072
	v_or_b32_e32 v74, 3, v151
	v_xad_u32 v75, v151, -4, v177
	v_or_b32_e32 v130, 4, v151
	v_xad_u32 v131, v151, -5, v177
	v_cndmask_b32_e64 v74, v75, v74, s[4:5]
	v_cndmask_b32_e64 v130, v131, v130, s[4:5]
	v_or_b32_e32 v132, 5, v151
	v_xad_u32 v133, v151, -6, v177
	v_add_u32_e32 v74, s52, v74
	v_add_u32_e32 v130, s52, v130
	v_cndmask_b32_e64 v132, v133, v132, s[4:5]
	v_mad_i64_i32 v[74:75], s[0:1], v74, s72, v[70:71]
	v_mad_i64_i32 v[130:131], s[0:1], v130, s72, v[70:71]
	v_add_u32_e32 v132, s52, v132
	v_lshl_add_u64 v[72:73], v[134:135], 0, v[92:93]
	v_lshl_add_u64 v[76:77], v[74:75], 0, v[82:83]
	v_lshl_add_u64 v[134:135], v[130:131], 0, v[82:83]
	v_lshl_add_u64 v[144:145], v[130:131], 0, v[0:1]
	v_mad_i64_i32 v[146:147], s[0:1], v132, s72, v[70:71]
	v_lshlrev_b32_e32 v160, 16, v136
	v_lshl_add_u64 v[128:129], v[74:75], 0, v[0:1]
	v_lshl_add_u64 v[74:75], v[74:75], 0, v[92:93]
	v_lshl_add_u64 v[130:131], v[130:131], 0, v[92:93]
	v_lshl_add_u64 v[148:149], v[146:147], 0, v[82:83]
	global_load_ushort v138, v[72:73], off
	global_load_ushort v132, v[76:77], off
	global_load_ushort v133, v[128:129], off offset:3072
	global_load_ushort v142, v[74:75], off
	s_nop 0
	global_load_ushort v134, v[134:135], off
	s_nop 0
	global_load_ushort v135, v[144:145], off offset:3072
	global_load_ushort v139, v[130:131], off
	global_load_ushort v136, v[148:149], off
	v_or_b32_e32 v76, 6, v151
	v_xad_u32 v77, v151, -7, v177
	v_or_b32_e32 v143, 7, v151
	v_xad_u32 v144, v151, -8, v177
	v_cndmask_b32_e64 v76, v77, v76, s[4:5]
	v_cndmask_b32_e64 v143, v144, v143, s[4:5]
	v_add_u32_e32 v76, s52, v76
	v_add_u32_e32 v143, s52, v143
	v_mul_f32_e32 v141, 0xbfb8aa3b, v141
	v_mad_i64_i32 v[76:77], s[0:1], v76, s72, v[70:71]
	v_mad_i64_i32 v[70:71], s[0:1], v143, s72, v[70:71]
	v_exp_f32_e32 v141, v141
	v_mul_f32_e32 v143, 0xbfb8aa3b, v150
	v_exp_f32_e32 v143, v143
	v_lshl_add_u64 v[72:73], v[146:147], 0, v[0:1]
	v_lshl_add_u64 v[74:75], v[146:147], 0, v[92:93]
	v_lshl_add_u64 v[128:129], v[76:77], 0, v[82:83]
	v_lshl_add_u64 v[130:131], v[76:77], 0, v[0:1]
	v_lshl_add_u64 v[76:77], v[76:77], 0, v[92:93]
	v_lshl_add_u64 v[146:147], v[70:71], 0, v[82:83]
	v_lshl_add_u64 v[148:149], v[70:71], 0, v[0:1]
	v_lshl_add_u64 v[70:71], v[70:71], 0, v[92:93]
	v_add_f32_e32 v93, 1.0, v141
	v_rcp_f32_e32 v150, v93
	v_add_f32_e32 v93, 1.0, v143
	v_rcp_f32_e32 v151, v93
	global_load_ushort v93, v[72:73], off offset:3072
	global_load_ushort v144, v[74:75], off
	s_nop 0
	global_load_ushort v128, v[128:129], off
	s_nop 0
	global_load_ushort v129, v[130:131], off offset:3072
	global_load_ushort v141, v[76:77], off
	s_nop 0
	global_load_ushort v130, v[146:147], off
	global_load_ushort v131, v[148:149], off offset:3072
	global_load_ushort v143, v[70:71], off
	v_mul_f32_e32 v70, 0xbfb8aa3b, v154
	v_exp_f32_e32 v72, v70
	v_mul_f32_e32 v73, 0xbfb8aa3b, v156
	v_exp_f32_e32 v73, v73
	v_pk_fma_f32 v[70:71], v[86:87], v[150:151], v[84:85]
	v_add_f32_e32 v72, 1.0, v72
	v_rcp_f32_e32 v72, v72
	v_sub_f32_e32 v75, 1.0, v71
	v_mul_f32_e32 v76, v70, v71
	v_mul_f32_e32 v149, 0xbfb8aa3b, v164
	v_fma_f32 v71, v86, v72, v84
	v_add_f32_e32 v72, 1.0, v73
	v_mul_f32_e32 v73, 0xbfb8aa3b, v158
	v_rcp_f32_e32 v72, v72
	v_exp_f32_e32 v73, v73
	v_sub_f32_e32 v77, 1.0, v71
	v_mul_f32_e32 v145, v76, v71
	v_fma_f32 v71, v86, v72, v84
	v_add_f32_e32 v72, 1.0, v73
	v_mul_f32_e32 v73, 0xbfb8aa3b, v160
	v_rcp_f32_e32 v72, v72
	v_exp_f32_e32 v73, v73
	v_sub_f32_e32 v146, 1.0, v71
	v_mul_f32_e32 v147, v145, v71
	v_fma_f32 v71, v86, v72, v84
	v_add_f32_e32 v72, 1.0, v73
	v_mul_f32_e32 v73, 0xbfb8aa3b, v162
	v_rcp_f32_e32 v72, v72
	v_exp_f32_e32 v73, v73
	v_exp_f32_e32 v149, v149
	v_mul_f32_e32 v148, v147, v71
	v_fma_f32 v150, v86, v72, v84
	v_add_f32_e32 v72, 1.0, v73
	v_rcp_f32_e32 v72, v72
	v_add_f32_e32 v73, 1.0, v149
	v_rcp_f32_e32 v73, v73
	v_mul_f32_e32 v149, v148, v150
	v_fma_f32 v151, v86, v72, v84
	v_mul_f32_e32 v154, v149, v151
	v_fma_f32 v156, v86, v73, v84
	v_mul_f32_e32 v158, v154, v156
	ds_write_b32 v101, v158 offset:17408
	s_waitcnt lgkmcnt(0)
	s_barrier
	ds_read2st64_b32 v[72:73], v102 offset0:68 offset1:70
	v_sub_f32_e32 v160, 1.0, v71
	v_sub_f32_e32 v71, 1.0, v151
	v_sub_f32_e32 v151, 1.0, v156
	v_sub_f32_e32 v74, 1.0, v70
	s_waitcnt lgkmcnt(0)
	v_cndmask_b32_e64 v156, v72, 1.0, vcc
	v_mul_f32_e32 v70, v70, v156
	v_rcp_f32_e32 v162, v70
	v_mul_f32_e32 v152, 0x3db504f3, v152
	v_mul_f32_e32 v70, v152, v70
	v_cvt_pk_bf16_f32 v70, v70, v1
	ds_write_b16 v110, v70
	v_mul_f32_e32 v152, v74, v162
	v_cvt_pk_bf16_f32 v70, v152, v1
	ds_write_b16 v110, v70 offset:4352
	v_mul_f32_e32 v70, v76, v156
	v_rcp_f32_e32 v74, v70
	v_mul_f32_e32 v76, 0x3db504f3, v153
	v_mul_f32_e32 v70, v76, v70
	v_cvt_pk_bf16_f32 v70, v70, v1
	ds_write_b16 v112, v70
	v_mul_f32_e32 v76, v75, v74
	v_cvt_pk_bf16_f32 v70, v76, v1
	ds_write_b16 v112, v70 offset:4352
	v_mul_f32_e32 v70, v145, v156
	v_rcp_f32_e32 v74, v70
	v_mul_f32_e32 v75, 0x3db504f3, v155
	v_mul_f32_e32 v70, v75, v70
	v_cvt_pk_bf16_f32 v70, v70, v1
	ds_write_b16 v114, v70
	v_mul_f32_e32 v77, v77, v74
	v_cvt_pk_bf16_f32 v70, v77, v1
	ds_write_b16 v114, v70 offset:4352
	v_mul_f32_e32 v70, v147, v156
	v_rcp_f32_e32 v74, v70
	v_mul_f32_e32 v75, 0x3db504f3, v157
	v_mul_f32_e32 v70, v75, v70
	v_cvt_pk_bf16_f32 v70, v70, v1
	ds_write_b16 v116, v70
	v_mul_f32_e32 v145, v146, v74
	v_cvt_pk_bf16_f32 v70, v145, v1
	ds_write_b16 v116, v70 offset:4352
	v_mul_f32_e32 v70, v148, v156
	v_rcp_f32_e32 v74, v70
	v_mul_f32_e32 v75, 0x3db504f3, v159
	v_mul_f32_e32 v70, v75, v70
	v_cvt_pk_bf16_f32 v70, v70, v1
	ds_write_b16 v117, v70
	v_mul_f32_e32 v146, v160, v74
	v_cvt_pk_bf16_f32 v70, v146, v1
	ds_write_b16 v117, v70 offset:4352
	v_mul_f32_e32 v70, v149, v156
	v_rcp_f32_e32 v74, v70
	v_mul_f32_e32 v75, 0x3db504f3, v161
	v_mul_f32_e32 v70, v75, v70
	v_sub_f32_e32 v150, 1.0, v150
	v_cvt_pk_bf16_f32 v70, v70, v1
	ds_write_b16 v119, v70
	v_mul_f32_e32 v147, v150, v74
	v_cvt_pk_bf16_f32 v70, v147, v1
	ds_write_b16 v119, v70 offset:4352
	v_mul_f32_e32 v70, v154, v156
	v_rcp_f32_e32 v75, v70
	v_mul_f32_e32 v74, 0x3db504f3, v163
	v_mul_f32_e32 v70, v74, v70
	v_cvt_pk_bf16_f32 v70, v70, v1
	ds_write_b16 v121, v70
	v_mov_b32_e32 v70, v72
	v_mov_b32_e32 v74, v73
	v_pk_mul_f32 v[70:71], v[70:71], v[74:75]
	s_nop 0
	v_mul_f32_e32 v75, v70, v145
	v_cvt_pk_bf16_f32 v145, v71, v1
	ds_write_b16 v121, v145 offset:4352
	v_mul_f32_e32 v145, v158, v156
	v_mul_f32_e32 v73, v70, v76
	v_mul_f32_e32 v76, v70, v146
	v_rcp_f32_e32 v146, v145
	v_mul_f32_e32 v74, v70, v77
	v_mul_f32_e32 v77, v70, v147
	v_mul_f32_e32 v147, 0x3db504f3, v165
	v_mul_f32_e32 v145, v147, v145
	v_cvt_pk_bf16_f32 v145, v145, v1
	v_mul_f32_e32 v72, v70, v152
	ds_write_b16 v122, v145
	v_mul_f32_e32 v145, v151, v146
	v_mul_f32_e32 v71, v70, v71
	v_cvt_pk_bf16_f32 v146, v145, v1
	ds_write_b16 v122, v146 offset:4352
	v_mul_f32_e32 v145, v70, v145
	v_cvt_pk_bf16_f32 v72, v72, v73
	v_cvt_pk_bf16_f32 v73, v74, v75
	v_cvt_pk_bf16_f32 v74, v76, v77
	v_cvt_pk_bf16_f32 v75, v71, v145
	ds_write_b128 v103, v[72:75] offset:8704
	ds_write_b128 v103, v[66:69] offset:12800
	s_and_saveexec_b64 s[54:55], vcc
	s_cbranch_execz .LBB0_264
	ds_write_b32 v126, v70 offset:16896
	s_branch .LBB0_264

	.amdhsa_kernel _Z8mega_fwd4Args
		.amdhsa_group_segment_fixed_size 0
		.amdhsa_private_segment_fixed_size 0
		.amdhsa_kernarg_size 512
		.amdhsa_user_sgpr_count 2
		.amdhsa_user_sgpr_dispatch_ptr 0
		.amdhsa_user_sgpr_queue_ptr 0
		.amdhsa_user_sgpr_kernarg_segment_ptr 1
		.amdhsa_user_sgpr_dispatch_id 0
		.amdhsa_user_sgpr_kernarg_preload_length 0
		.amdhsa_user_sgpr_kernarg_preload_offset 0
		.amdhsa_user_sgpr_private_segment_size 0
		.amdhsa_uses_dynamic_stack 0
		.amdhsa_enable_private_segment 0
		.amdhsa_system_sgpr_workgroup_id_x 1
		.amdhsa_system_sgpr_workgroup_id_y 0
		.amdhsa_system_sgpr_workgroup_id_z 0
		.amdhsa_system_sgpr_workgroup_info 0
		.amdhsa_system_vgpr_workitem_id 2
		.amdhsa_next_free_vgpr 227
		.amdhsa_next_free_sgpr 102
		.amdhsa_accum_offset 228
		.amdhsa_reserve_vcc 1
		.amdhsa_float_round_mode_32 0
		.amdhsa_float_round_mode_16_64 0
		.amdhsa_float_denorm_mode_32 3
		.amdhsa_float_denorm_mode_16_64 3
		.amdhsa_dx10_clamp 1
		.amdhsa_ieee_mode 1
		.amdhsa_fp16_overflow 0
		.amdhsa_tg_split 0
		.amdhsa_exception_fp_ieee_invalid_op 0
		.amdhsa_exception_fp_denorm_src 0
		.amdhsa_exception_fp_ieee_div_zero 0
		.amdhsa_exception_fp_ieee_overflow 0
		.amdhsa_exception_fp_ieee_underflow 0
		.amdhsa_exception_fp_ieee_inexact 0
		.amdhsa_exception_int_div_zero 0
	.end_amdhsa_kernel

amdhsa.kernels:
  - .agpr_count:     0
    .args:
      - .offset:         0
        .size:           256
        .value_kind:     by_value
      - .offset:         256
        .size:           4
        .value_kind:     hidden_block_count_x
      - .offset:         260
        .size:           4
        .value_kind:     hidden_block_count_y
      - .offset:         264
        .size:           4
        .value_kind:     hidden_block_count_z
      - .offset:         268
        .size:           2
        .value_kind:     hidden_group_size_x
      - .offset:         270
        .size:           2
        .value_kind:     hidden_group_size_y
      - .offset:         272
        .size:           2
        .value_kind:     hidden_group_size_z
      - .offset:         274
        .size:           2
        .value_kind:     hidden_remainder_x
      - .offset:         276
        .size:           2
        .value_kind:     hidden_remainder_y
      - .offset:         278
        .size:           2
        .value_kind:     hidden_remainder_z
      - .offset:         296
        .size:           8
        .value_kind:     hidden_global_offset_x
      - .offset:         304
        .size:           8
        .value_kind:     hidden_global_offset_y
      - .offset:         312
        .size:           8
        .value_kind:     hidden_global_offset_z
      - .offset:         320
        .size:           2
        .value_kind:     hidden_grid_dims
      - .offset:         344
        .size:           8
        .value_kind:     hidden_multigrid_sync_arg
      - .offset:         376
        .size:           4
        .value_kind:     hidden_dynamic_lds_size
    .group_segment_fixed_size: 0
    .kernarg_segment_align: 8
    .kernarg_segment_size: 512
    .language:       OpenCL C
    .language_version:
      - 2
      - 0
    .max_flat_workgroup_size: 512
    .name:           _Z8mega_fwd4Args
    .private_segment_fixed_size: 0
    .sgpr_count:     108
    .sgpr_spill_count: 14
    .symbol:         _Z8mega_fwd4Args.kd
    .uniform_work_group_size: 1
    .uses_dynamic_stack: false
    .vgpr_count:     227
    .vgpr_spill_count: 0
    .wavefront_size: 64
